# first K iteration of the up and residual main loops peeled with zero addend, per-unit accumulator zero fill removed; MFMA runs re-padded
# speedup vs baseline: 1.0109x; 1.0109x over previous
.LBB0_103:
	s_ashr_i32 s23, s22, 31
	s_lshl_b64 s[2:3], s[22:23], 19
	s_add_u32 s58, s90, s2
	s_addc_u32 s59, s77, s3
	s_and_b64 s[2:3], s[46:47], exec
	s_cselect_b32 s1, s59, s49
	s_cselect_b32 s23, s58, s48
	s_add_u32 s34, s34, 0x3e080
	s_addc_u32 s35, s35, 0
	s_add_u32 s51, s48, 0x100
	v_mov_b32_e32 v2, 0
	s_addc_u32 s52, s49, 0
	s_mov_b32 s53, -2
	s_add_u32 s2, s34, 0xfffc2080
	s_addc_u32 s3, s35, -1
	s_add_i32 s12, 0, 0x10000
	v_add_u32_e32 v110, s12, v179
	ds_read_b128 v[98:101], v110
	ds_read_b128 v[102:105], v110 offset:1024
	ds_read_b128 v[106:109], v110 offset:2048
	ds_read_b128 v[110:113], v110 offset:3072
	s_cmp_eq_u32 s53, 12
	s_cselect_b32 s49, s97, s3
	s_cselect_b32 s48, s96, s2
	s_cselect_b32 s3, s1, s52
	s_cselect_b32 s2, s23, s51
	v_lshl_add_u64 v[174:175], s[34:35], 0, v[170:171]
	s_add_i32 m0, s85, 0xc000
	ds_read_b128 v[114:117], v184
	ds_read_b128 v[118:121], v184 offset:1024
	ds_read_b128 v[122:125], v184 offset:2048
	ds_read_b128 v[126:129], v184 offset:3072
	ds_read_b128 v[186:189], v184 offset:4096
	ds_read_b128 v[190:193], v184 offset:5120
	ds_read_b128 v[194:197], v184 offset:6144
	ds_read_b128 v[198:201], v184 offset:7168
	global_load_lds_dwordx4 v[174:175], off
	v_lshl_add_u64 v[174:175], s[34:35], 0, v[172:173]
	s_add_i32 m0, s85, 0xe000
	s_nop 0
	global_load_lds_dwordx4 v[174:175], off
	s_waitcnt lgkmcnt(8)
	s_add_i32 s54, 0, 0x14000
	v_add_u32_e32 v174, s54, v179
	s_add_i32 s12, s12, s78
	ds_read_b128 v[226:229], v174
	ds_read_b128 v[230:233], v174 offset:1024
	ds_read_b128 v[234:237], v174 offset:2048
	ds_read_b128 v[242:245], v174 offset:3072
	s_barrier
	s_waitcnt lgkmcnt(0)
	s_waitcnt lgkmcnt(0)
	s_nop 0
	v_mfma_f32_16x16x32_bf16 v[158:161], v[98:101], v[114:117], 0
	v_mfma_f32_16x16x32_bf16 v[154:157], v[106:109], v[114:117], 0
	v_mfma_f32_16x16x32_bf16 v[150:153], v[98:101], v[122:125], 0
	v_mfma_f32_16x16x32_bf16 v[146:149], v[106:109], v[122:125], 0
	v_mfma_f32_16x16x32_bf16 v[142:145], v[98:101], v[186:189], 0
	v_mfma_f32_16x16x32_bf16 v[138:141], v[106:109], v[186:189], 0
	v_mfma_f32_16x16x32_bf16 v[134:137], v[98:101], v[194:197], 0
	v_mfma_f32_16x16x32_bf16 v[130:133], v[106:109], v[194:197], 0
	v_mfma_f32_16x16x32_bf16 v[158:161], v[102:105], v[118:121], v[158:161]
	v_mfma_f32_16x16x32_bf16 v[154:157], v[110:113], v[118:121], v[154:157]
	v_mfma_f32_16x16x32_bf16 v[150:153], v[102:105], v[126:129], v[150:153]
	v_mfma_f32_16x16x32_bf16 v[146:149], v[110:113], v[126:129], v[146:149]
	v_mfma_f32_16x16x32_bf16 v[142:145], v[102:105], v[190:193], v[142:145]
	v_mfma_f32_16x16x32_bf16 v[138:141], v[110:113], v[190:193], v[138:141]
	v_mfma_f32_16x16x32_bf16 v[134:137], v[102:105], v[198:201], v[134:137]
	v_mfma_f32_16x16x32_bf16 v[130:133], v[110:113], v[198:201], v[130:133]
	s_waitcnt lgkmcnt(0)
	s_waitcnt lgkmcnt(0)
	v_mfma_f32_16x16x32_bf16 v[62:65], v[226:229], v[114:117], 0
	v_mfma_f32_16x16x32_bf16 v[58:61], v[234:237], v[114:117], 0
	v_mfma_f32_16x16x32_bf16 v[54:57], v[226:229], v[122:125], 0
	v_mfma_f32_16x16x32_bf16 v[50:53], v[234:237], v[122:125], 0
	v_mfma_f32_16x16x32_bf16 v[46:49], v[226:229], v[186:189], 0
	v_mfma_f32_16x16x32_bf16 v[42:45], v[234:237], v[186:189], 0
	v_mfma_f32_16x16x32_bf16 v[38:41], v[226:229], v[194:197], 0
	v_mfma_f32_16x16x32_bf16 v[34:37], v[234:237], v[194:197], 0
	v_mfma_f32_16x16x32_bf16 v[62:65], v[230:233], v[118:121], v[62:65]
	v_mfma_f32_16x16x32_bf16 v[58:61], v[242:245], v[118:121], v[58:61]
	v_mfma_f32_16x16x32_bf16 v[54:57], v[230:233], v[126:129], v[54:57]
	v_mfma_f32_16x16x32_bf16 v[50:53], v[242:245], v[126:129], v[50:53]
	v_mfma_f32_16x16x32_bf16 v[46:49], v[230:233], v[190:193], v[46:49]
	v_mfma_f32_16x16x32_bf16 v[42:45], v[242:245], v[190:193], v[42:45]
	v_mfma_f32_16x16x32_bf16 v[38:41], v[230:233], v[198:201], v[38:41]
	v_mfma_f32_16x16x32_bf16 v[34:37], v[242:245], v[198:201], v[34:37]
	s_mov_b32 m0, s85
	v_lshl_add_u64 v[248:249], s[48:49], 0, v[162:163]
	s_barrier
	ds_read_b128 v[114:117], v184 offset:16384
	ds_read_b128 v[118:121], v184 offset:17408
	ds_read_b128 v[122:125], v184 offset:18432
	ds_read_b128 v[126:129], v184 offset:19456
	ds_read_b128 v[186:189], v184 offset:20480
	ds_read_b128 v[190:193], v184 offset:21504
	ds_read_b128 v[194:197], v184 offset:22528
	ds_read_b128 v[198:201], v184 offset:23552
	global_load_lds_dwordx4 v[248:249], off
	v_lshl_add_u64 v[250:251], s[48:49], 0, v[164:165]
	s_mov_b32 m0, s82
	s_nop 0
	global_load_lds_dwordx4 v[250:251], off
	v_lshl_add_u64 v[174:175], s[2:3], 0, v[0:1]
	s_mov_b32 m0, s12
	v_lshl_add_u64 v[246:247], s[2:3], 0, v[166:167]
	global_load_lds_dwordx4 v[174:175], off
	s_add_i32 m0, s12, 0x2000
	s_nop 0
	global_load_lds_dwordx4 v[246:247], off
	s_add_u32 s12, s2, 0x40000
	s_addc_u32 s13, s3, 0
	s_add_i32 s54, s54, s78
	v_lshl_add_u64 v[174:175], s[12:13], 0, v[0:1]
	s_mov_b32 m0, s54
	s_nop 0
	global_load_lds_dwordx4 v[174:175], off
	v_lshl_add_u64 v[174:175], s[12:13], 0, v[166:167]
	s_add_i32 m0, s54, 0x2000
	s_nop 0
	global_load_lds_dwordx4 v[174:175], off
	s_waitcnt vmcnt(6)
	s_barrier
	s_waitcnt lgkmcnt(0)
	s_waitcnt lgkmcnt(0)
	s_nop 0
	v_mfma_f32_16x16x32_bf16 v[94:97], v[98:101], v[114:117], 0
	v_mfma_f32_16x16x32_bf16 v[90:93], v[106:109], v[114:117], 0
	v_mfma_f32_16x16x32_bf16 v[86:89], v[98:101], v[122:125], 0
	v_mfma_f32_16x16x32_bf16 v[82:85], v[106:109], v[122:125], 0
	v_mfma_f32_16x16x32_bf16 v[78:81], v[98:101], v[186:189], 0
	v_mfma_f32_16x16x32_bf16 v[74:77], v[106:109], v[186:189], 0
	v_mfma_f32_16x16x32_bf16 v[70:73], v[98:101], v[194:197], 0
	v_mfma_f32_16x16x32_bf16 v[66:69], v[106:109], v[194:197], 0
	v_mfma_f32_16x16x32_bf16 v[94:97], v[102:105], v[118:121], v[94:97]
	v_mfma_f32_16x16x32_bf16 v[90:93], v[110:113], v[118:121], v[90:93]
	v_mfma_f32_16x16x32_bf16 v[86:89], v[102:105], v[126:129], v[86:89]
	v_mfma_f32_16x16x32_bf16 v[82:85], v[110:113], v[126:129], v[82:85]
	v_mfma_f32_16x16x32_bf16 v[78:81], v[102:105], v[190:193], v[78:81]
	v_mfma_f32_16x16x32_bf16 v[74:77], v[110:113], v[190:193], v[74:77]
	v_mfma_f32_16x16x32_bf16 v[70:73], v[102:105], v[198:201], v[70:73]
	v_mfma_f32_16x16x32_bf16 v[66:69], v[110:113], v[198:201], v[66:69]
	v_mfma_f32_16x16x32_bf16 v[30:33], v[226:229], v[114:117], 0
	v_mfma_f32_16x16x32_bf16 v[26:29], v[234:237], v[114:117], 0
	v_mfma_f32_16x16x32_bf16 v[22:25], v[226:229], v[122:125], 0
	v_mfma_f32_16x16x32_bf16 v[18:21], v[234:237], v[122:125], 0
	v_mfma_f32_16x16x32_bf16 v[14:17], v[226:229], v[186:189], 0
	v_mfma_f32_16x16x32_bf16 v[10:13], v[234:237], v[186:189], 0
	v_mfma_f32_16x16x32_bf16 v[6:9], v[226:229], v[194:197], 0
	v_mfma_f32_16x16x32_bf16 v[2:5], v[234:237], v[194:197], 0
	v_mfma_f32_16x16x32_bf16 v[30:33], v[230:233], v[118:121], v[30:33]
	v_mfma_f32_16x16x32_bf16 v[26:29], v[242:245], v[118:121], v[26:29]
	v_mfma_f32_16x16x32_bf16 v[22:25], v[230:233], v[126:129], v[22:25]
	v_mfma_f32_16x16x32_bf16 v[18:21], v[242:245], v[126:129], v[18:21]
	v_mfma_f32_16x16x32_bf16 v[14:17], v[230:233], v[190:193], v[14:17]
	v_mfma_f32_16x16x32_bf16 v[10:13], v[242:245], v[190:193], v[10:13]
	v_mfma_f32_16x16x32_bf16 v[6:9], v[230:233], v[198:201], v[6:9]
	v_mfma_f32_16x16x32_bf16 v[2:5], v[242:245], v[198:201], v[2:5]
	s_add_i32 s54, 0, 0x18000
	v_add_u32_e32 v110, s54, v179
	s_barrier
	ds_read_b128 v[98:101], v110
	ds_read_b128 v[102:105], v110 offset:1024
	ds_read_b128 v[106:109], v110 offset:2048
	ds_read_b128 v[110:113], v110 offset:3072
	s_add_u32 s12, s48, 0x3e000
	s_addc_u32 s13, s49, 0
	s_mov_b32 m0, s89
	v_lshl_add_u64 v[226:227], s[12:13], 0, v[162:163]
	ds_read_b128 v[114:117], v184 offset:32768
	ds_read_b128 v[118:121], v184 offset:33792
	ds_read_b128 v[122:125], v184 offset:34816
	ds_read_b128 v[126:129], v184 offset:35840
	ds_read_b128 v[186:189], v184 offset:36864
	ds_read_b128 v[190:193], v184 offset:37888
	ds_read_b128 v[194:197], v184 offset:38912
	ds_read_b128 v[198:201], v184 offset:39936
	global_load_lds_dwordx4 v[226:227], off
	v_lshl_add_u64 v[226:227], s[12:13], 0, v[164:165]
	s_mov_b32 m0, s91
	s_nop 0
	global_load_lds_dwordx4 v[226:227], off
	s_waitcnt lgkmcnt(8)
	s_add_i32 s12, 0, 0x1c000
	s_add_i32 s13, s54, s78
	v_add_u32_e32 v242, s12, v179
	ds_read_b128 v[226:229], v242
	ds_read_b128 v[230:233], v242 offset:1024
	ds_read_b128 v[234:237], v242 offset:2048
	ds_read_b128 v[242:245], v242 offset:3072
	s_barrier
	s_waitcnt lgkmcnt(0)
	s_waitcnt lgkmcnt(0)
	v_mfma_f32_16x16x32_bf16 v[158:161], v[98:101], v[114:117], v[158:161]
	v_mfma_f32_16x16x32_bf16 v[154:157], v[106:109], v[114:117], v[154:157]
	v_mfma_f32_16x16x32_bf16 v[150:153], v[98:101], v[122:125], v[150:153]
	v_mfma_f32_16x16x32_bf16 v[146:149], v[106:109], v[122:125], v[146:149]
	v_mfma_f32_16x16x32_bf16 v[142:145], v[98:101], v[186:189], v[142:145]
	v_mfma_f32_16x16x32_bf16 v[138:141], v[106:109], v[186:189], v[138:141]
	v_mfma_f32_16x16x32_bf16 v[134:137], v[98:101], v[194:197], v[134:137]
	v_mfma_f32_16x16x32_bf16 v[130:133], v[106:109], v[194:197], v[130:133]
	v_mfma_f32_16x16x32_bf16 v[158:161], v[102:105], v[118:121], v[158:161]
	v_mfma_f32_16x16x32_bf16 v[154:157], v[110:113], v[118:121], v[154:157]
	v_mfma_f32_16x16x32_bf16 v[150:153], v[102:105], v[126:129], v[150:153]
	v_mfma_f32_16x16x32_bf16 v[146:149], v[110:113], v[126:129], v[146:149]
	v_mfma_f32_16x16x32_bf16 v[142:145], v[102:105], v[190:193], v[142:145]
	v_mfma_f32_16x16x32_bf16 v[138:141], v[110:113], v[190:193], v[138:141]
	v_mfma_f32_16x16x32_bf16 v[134:137], v[102:105], v[198:201], v[134:137]
	v_mfma_f32_16x16x32_bf16 v[130:133], v[110:113], v[198:201], v[130:133]
	s_waitcnt lgkmcnt(0)
	s_waitcnt lgkmcnt(0)
	v_mfma_f32_16x16x32_bf16 v[62:65], v[226:229], v[114:117], v[62:65]
	v_mfma_f32_16x16x32_bf16 v[58:61], v[234:237], v[114:117], v[58:61]
	v_mfma_f32_16x16x32_bf16 v[54:57], v[226:229], v[122:125], v[54:57]
	v_mfma_f32_16x16x32_bf16 v[50:53], v[234:237], v[122:125], v[50:53]
	v_mfma_f32_16x16x32_bf16 v[46:49], v[226:229], v[186:189], v[46:49]
	v_mfma_f32_16x16x32_bf16 v[42:45], v[234:237], v[186:189], v[42:45]
	v_mfma_f32_16x16x32_bf16 v[38:41], v[226:229], v[194:197], v[38:41]
	v_mfma_f32_16x16x32_bf16 v[34:37], v[234:237], v[194:197], v[34:37]
	v_mfma_f32_16x16x32_bf16 v[62:65], v[230:233], v[118:121], v[62:65]
	v_mfma_f32_16x16x32_bf16 v[58:61], v[242:245], v[118:121], v[58:61]
	v_mfma_f32_16x16x32_bf16 v[54:57], v[230:233], v[126:129], v[54:57]
	v_mfma_f32_16x16x32_bf16 v[50:53], v[242:245], v[126:129], v[50:53]
	v_mfma_f32_16x16x32_bf16 v[46:49], v[230:233], v[190:193], v[46:49]
	v_mfma_f32_16x16x32_bf16 v[42:45], v[242:245], v[190:193], v[42:45]
	v_mfma_f32_16x16x32_bf16 v[38:41], v[230:233], v[198:201], v[38:41]
	v_mfma_f32_16x16x32_bf16 v[34:37], v[242:245], v[198:201], v[34:37]
	s_mov_b32 m0, s79
	v_lshl_add_u64 v[174:175], v[248:249], 0, s[20:21]
	s_barrier
	ds_read_b128 v[114:117], v184 offset:49152
	ds_read_b128 v[118:121], v184 offset:50176
	ds_read_b128 v[122:125], v184 offset:51200
	ds_read_b128 v[126:129], v184 offset:52224
	ds_read_b128 v[186:189], v184 offset:53248
	ds_read_b128 v[190:193], v184 offset:54272
	ds_read_b128 v[194:197], v184 offset:55296
	ds_read_b128 v[198:201], v184 offset:56320
	global_load_lds_dwordx4 v[174:175], off
	v_lshl_add_u64 v[174:175], v[250:251], 0, s[20:21]
	s_mov_b32 m0, s87
	s_nop 0
	global_load_lds_dwordx4 v[174:175], off
	v_lshl_add_u64 v[174:175], s[2:3], 0, v[0:1]
	v_lshl_add_u64 v[174:175], v[174:175], 0, s[20:21]
	s_mov_b32 m0, s13
	s_nop 0
	global_load_lds_dwordx4 v[174:175], off
	v_lshl_add_u64 v[174:175], v[246:247], 0, s[20:21]
	s_add_i32 m0, s13, 0x2000
	s_nop 0
	global_load_lds_dwordx4 v[174:175], off
	s_add_u32 s2, s2, 0x40080
	s_addc_u32 s3, s3, 0
	s_add_i32 s12, s12, s78
	v_lshl_add_u64 v[174:175], s[2:3], 0, v[0:1]
	s_mov_b32 m0, s12
	s_nop 0
	global_load_lds_dwordx4 v[174:175], off
	v_lshl_add_u64 v[174:175], s[2:3], 0, v[166:167]
	s_add_i32 m0, s12, 0x2000
	s_nop 0
	global_load_lds_dwordx4 v[174:175], off
	s_waitcnt vmcnt(6)
	s_barrier
	s_waitcnt lgkmcnt(0)
	s_waitcnt lgkmcnt(0)
	v_mfma_f32_16x16x32_bf16 v[94:97], v[98:101], v[114:117], v[94:97]
	v_mfma_f32_16x16x32_bf16 v[90:93], v[106:109], v[114:117], v[90:93]
	v_mfma_f32_16x16x32_bf16 v[86:89], v[98:101], v[122:125], v[86:89]
	v_mfma_f32_16x16x32_bf16 v[82:85], v[106:109], v[122:125], v[82:85]
	v_mfma_f32_16x16x32_bf16 v[78:81], v[98:101], v[186:189], v[78:81]
	v_mfma_f32_16x16x32_bf16 v[74:77], v[106:109], v[186:189], v[74:77]
	v_mfma_f32_16x16x32_bf16 v[70:73], v[98:101], v[194:197], v[70:73]
	v_mfma_f32_16x16x32_bf16 v[66:69], v[106:109], v[194:197], v[66:69]
	v_mfma_f32_16x16x32_bf16 v[94:97], v[102:105], v[118:121], v[94:97]
	v_mfma_f32_16x16x32_bf16 v[90:93], v[110:113], v[118:121], v[90:93]
	v_mfma_f32_16x16x32_bf16 v[86:89], v[102:105], v[126:129], v[86:89]
	v_mfma_f32_16x16x32_bf16 v[82:85], v[110:113], v[126:129], v[82:85]
	v_mfma_f32_16x16x32_bf16 v[78:81], v[102:105], v[190:193], v[78:81]
	v_mfma_f32_16x16x32_bf16 v[74:77], v[110:113], v[190:193], v[74:77]
	v_mfma_f32_16x16x32_bf16 v[70:73], v[102:105], v[198:201], v[70:73]
	v_mfma_f32_16x16x32_bf16 v[66:69], v[110:113], v[198:201], v[66:69]
	v_mfma_f32_16x16x32_bf16 v[30:33], v[226:229], v[114:117], v[30:33]
	v_mfma_f32_16x16x32_bf16 v[26:29], v[234:237], v[114:117], v[26:29]
	v_mfma_f32_16x16x32_bf16 v[22:25], v[226:229], v[122:125], v[22:25]
	v_mfma_f32_16x16x32_bf16 v[18:21], v[234:237], v[122:125], v[18:21]
	v_mfma_f32_16x16x32_bf16 v[14:17], v[226:229], v[186:189], v[14:17]
	v_mfma_f32_16x16x32_bf16 v[10:13], v[234:237], v[186:189], v[10:13]
	v_mfma_f32_16x16x32_bf16 v[6:9], v[226:229], v[194:197], v[6:9]
	v_mfma_f32_16x16x32_bf16 v[2:5], v[234:237], v[194:197], v[2:5]
	v_mfma_f32_16x16x32_bf16 v[30:33], v[230:233], v[118:121], v[30:33]
	v_mfma_f32_16x16x32_bf16 v[26:29], v[242:245], v[118:121], v[26:29]
	v_mfma_f32_16x16x32_bf16 v[22:25], v[230:233], v[126:129], v[22:25]
	v_mfma_f32_16x16x32_bf16 v[18:21], v[242:245], v[126:129], v[18:21]
	v_mfma_f32_16x16x32_bf16 v[14:17], v[230:233], v[190:193], v[14:17]
	v_mfma_f32_16x16x32_bf16 v[10:13], v[242:245], v[190:193], v[10:13]
	v_mfma_f32_16x16x32_bf16 v[6:9], v[230:233], v[198:201], v[6:9]
	v_mfma_f32_16x16x32_bf16 v[2:5], v[242:245], v[198:201], v[2:5]
	s_add_i32 s53, s53, 2
	s_add_u32 s34, s34, 0x100
	s_addc_u32 s35, s35, 0
	s_add_u32 s51, s51, 0x100
	s_addc_u32 s52, s52, 0
	s_cmp_gt_u32 s53, 13
	s_barrier
	s_cbranch_scc1 .Lpeel_x_0
.LBB0_104:
	s_add_u32 s2, s34, 0xfffc2080
	s_addc_u32 s3, s35, -1
	s_add_i32 s12, 0, 0x10000
	v_add_u32_e32 v110, s12, v179
	ds_read_b128 v[98:101], v110
	ds_read_b128 v[102:105], v110 offset:1024
	ds_read_b128 v[106:109], v110 offset:2048
	ds_read_b128 v[110:113], v110 offset:3072
	s_cmp_eq_u32 s53, 12
	s_cselect_b32 s49, s97, s3
	s_cselect_b32 s48, s96, s2
	s_cselect_b32 s3, s1, s52
	s_cselect_b32 s2, s23, s51
	v_lshl_add_u64 v[174:175], s[34:35], 0, v[170:171]
	s_add_i32 m0, s85, 0xc000
	ds_read_b128 v[114:117], v184
	ds_read_b128 v[118:121], v184 offset:1024
	ds_read_b128 v[122:125], v184 offset:2048
	ds_read_b128 v[126:129], v184 offset:3072
	ds_read_b128 v[186:189], v184 offset:4096
	ds_read_b128 v[190:193], v184 offset:5120
	ds_read_b128 v[194:197], v184 offset:6144
	ds_read_b128 v[198:201], v184 offset:7168
	global_load_lds_dwordx4 v[174:175], off
	v_lshl_add_u64 v[174:175], s[34:35], 0, v[172:173]
	s_add_i32 m0, s85, 0xe000
	s_nop 0
	global_load_lds_dwordx4 v[174:175], off
	s_waitcnt lgkmcnt(8)
	s_add_i32 s54, 0, 0x14000
	v_add_u32_e32 v174, s54, v179
	s_add_i32 s12, s12, s78
	ds_read_b128 v[226:229], v174
	ds_read_b128 v[230:233], v174 offset:1024
	ds_read_b128 v[234:237], v174 offset:2048
	ds_read_b128 v[242:245], v174 offset:3072
	s_barrier
	s_waitcnt lgkmcnt(0)
	s_waitcnt lgkmcnt(0)
	v_mfma_f32_16x16x32_bf16 v[158:161], v[98:101], v[114:117], v[158:161]
	v_mfma_f32_16x16x32_bf16 v[154:157], v[106:109], v[114:117], v[154:157]
	v_mfma_f32_16x16x32_bf16 v[150:153], v[98:101], v[122:125], v[150:153]
	v_mfma_f32_16x16x32_bf16 v[146:149], v[106:109], v[122:125], v[146:149]
	v_mfma_f32_16x16x32_bf16 v[142:145], v[98:101], v[186:189], v[142:145]
	v_mfma_f32_16x16x32_bf16 v[138:141], v[106:109], v[186:189], v[138:141]
	v_mfma_f32_16x16x32_bf16 v[134:137], v[98:101], v[194:197], v[134:137]
	v_mfma_f32_16x16x32_bf16 v[130:133], v[106:109], v[194:197], v[130:133]
	v_mfma_f32_16x16x32_bf16 v[158:161], v[102:105], v[118:121], v[158:161]
	v_mfma_f32_16x16x32_bf16 v[154:157], v[110:113], v[118:121], v[154:157]
	v_mfma_f32_16x16x32_bf16 v[150:153], v[102:105], v[126:129], v[150:153]
	v_mfma_f32_16x16x32_bf16 v[146:149], v[110:113], v[126:129], v[146:149]
	v_mfma_f32_16x16x32_bf16 v[142:145], v[102:105], v[190:193], v[142:145]
	v_mfma_f32_16x16x32_bf16 v[138:141], v[110:113], v[190:193], v[138:141]
	v_mfma_f32_16x16x32_bf16 v[134:137], v[102:105], v[198:201], v[134:137]
	v_mfma_f32_16x16x32_bf16 v[130:133], v[110:113], v[198:201], v[130:133]
	s_waitcnt lgkmcnt(0)
	s_waitcnt lgkmcnt(0)
	v_mfma_f32_16x16x32_bf16 v[62:65], v[226:229], v[114:117], v[62:65]
	v_mfma_f32_16x16x32_bf16 v[58:61], v[234:237], v[114:117], v[58:61]
	v_mfma_f32_16x16x32_bf16 v[54:57], v[226:229], v[122:125], v[54:57]
	v_mfma_f32_16x16x32_bf16 v[50:53], v[234:237], v[122:125], v[50:53]
	v_mfma_f32_16x16x32_bf16 v[46:49], v[226:229], v[186:189], v[46:49]
	v_mfma_f32_16x16x32_bf16 v[42:45], v[234:237], v[186:189], v[42:45]
	v_mfma_f32_16x16x32_bf16 v[38:41], v[226:229], v[194:197], v[38:41]
	v_mfma_f32_16x16x32_bf16 v[34:37], v[234:237], v[194:197], v[34:37]
	v_mfma_f32_16x16x32_bf16 v[62:65], v[230:233], v[118:121], v[62:65]
	v_mfma_f32_16x16x32_bf16 v[58:61], v[242:245], v[118:121], v[58:61]
	v_mfma_f32_16x16x32_bf16 v[54:57], v[230:233], v[126:129], v[54:57]
	v_mfma_f32_16x16x32_bf16 v[50:53], v[242:245], v[126:129], v[50:53]
	v_mfma_f32_16x16x32_bf16 v[46:49], v[230:233], v[190:193], v[46:49]
	v_mfma_f32_16x16x32_bf16 v[42:45], v[242:245], v[190:193], v[42:45]
	v_mfma_f32_16x16x32_bf16 v[38:41], v[230:233], v[198:201], v[38:41]
	v_mfma_f32_16x16x32_bf16 v[34:37], v[242:245], v[198:201], v[34:37]
	s_mov_b32 m0, s85
	v_lshl_add_u64 v[248:249], s[48:49], 0, v[162:163]
	s_barrier
	ds_read_b128 v[114:117], v184 offset:16384
	ds_read_b128 v[118:121], v184 offset:17408
	ds_read_b128 v[122:125], v184 offset:18432
	ds_read_b128 v[126:129], v184 offset:19456
	ds_read_b128 v[186:189], v184 offset:20480
	ds_read_b128 v[190:193], v184 offset:21504
	ds_read_b128 v[194:197], v184 offset:22528
	ds_read_b128 v[198:201], v184 offset:23552
	global_load_lds_dwordx4 v[248:249], off
	v_lshl_add_u64 v[250:251], s[48:49], 0, v[164:165]
	s_mov_b32 m0, s82
	s_nop 0
	global_load_lds_dwordx4 v[250:251], off
	v_lshl_add_u64 v[174:175], s[2:3], 0, v[0:1]
	s_mov_b32 m0, s12
	v_lshl_add_u64 v[246:247], s[2:3], 0, v[166:167]
	global_load_lds_dwordx4 v[174:175], off
	s_add_i32 m0, s12, 0x2000
	s_nop 0
	global_load_lds_dwordx4 v[246:247], off
	s_add_u32 s12, s2, 0x40000
	s_addc_u32 s13, s3, 0
	s_add_i32 s54, s54, s78
	v_lshl_add_u64 v[174:175], s[12:13], 0, v[0:1]
	s_mov_b32 m0, s54
	s_nop 0
	global_load_lds_dwordx4 v[174:175], off
	v_lshl_add_u64 v[174:175], s[12:13], 0, v[166:167]
	s_add_i32 m0, s54, 0x2000
	s_nop 0
	global_load_lds_dwordx4 v[174:175], off
	s_waitcnt vmcnt(6)
	s_barrier
	s_waitcnt lgkmcnt(0)
	s_waitcnt lgkmcnt(0)
	s_nop 0
	v_mfma_f32_16x16x32_bf16 v[94:97], v[98:101], v[114:117], v[94:97]
	v_mfma_f32_16x16x32_bf16 v[90:93], v[106:109], v[114:117], v[90:93]
	v_mfma_f32_16x16x32_bf16 v[86:89], v[98:101], v[122:125], v[86:89]
	v_mfma_f32_16x16x32_bf16 v[82:85], v[106:109], v[122:125], v[82:85]
	v_mfma_f32_16x16x32_bf16 v[78:81], v[98:101], v[186:189], v[78:81]
	v_mfma_f32_16x16x32_bf16 v[74:77], v[106:109], v[186:189], v[74:77]
	v_mfma_f32_16x16x32_bf16 v[70:73], v[98:101], v[194:197], v[70:73]
	v_mfma_f32_16x16x32_bf16 v[66:69], v[106:109], v[194:197], v[66:69]
	v_mfma_f32_16x16x32_bf16 v[94:97], v[102:105], v[118:121], v[94:97]
	v_mfma_f32_16x16x32_bf16 v[90:93], v[110:113], v[118:121], v[90:93]
	v_mfma_f32_16x16x32_bf16 v[86:89], v[102:105], v[126:129], v[86:89]
	v_mfma_f32_16x16x32_bf16 v[82:85], v[110:113], v[126:129], v[82:85]
	v_mfma_f32_16x16x32_bf16 v[78:81], v[102:105], v[190:193], v[78:81]
	v_mfma_f32_16x16x32_bf16 v[74:77], v[110:113], v[190:193], v[74:77]
	v_mfma_f32_16x16x32_bf16 v[70:73], v[102:105], v[198:201], v[70:73]
	v_mfma_f32_16x16x32_bf16 v[66:69], v[110:113], v[198:201], v[66:69]
	v_mfma_f32_16x16x32_bf16 v[30:33], v[226:229], v[114:117], v[30:33]
	v_mfma_f32_16x16x32_bf16 v[26:29], v[234:237], v[114:117], v[26:29]
	v_mfma_f32_16x16x32_bf16 v[22:25], v[226:229], v[122:125], v[22:25]
	v_mfma_f32_16x16x32_bf16 v[18:21], v[234:237], v[122:125], v[18:21]
	v_mfma_f32_16x16x32_bf16 v[14:17], v[226:229], v[186:189], v[14:17]
	v_mfma_f32_16x16x32_bf16 v[10:13], v[234:237], v[186:189], v[10:13]
	v_mfma_f32_16x16x32_bf16 v[6:9], v[226:229], v[194:197], v[6:9]
	v_mfma_f32_16x16x32_bf16 v[2:5], v[234:237], v[194:197], v[2:5]
	v_mfma_f32_16x16x32_bf16 v[30:33], v[230:233], v[118:121], v[30:33]
	v_mfma_f32_16x16x32_bf16 v[26:29], v[242:245], v[118:121], v[26:29]
	v_mfma_f32_16x16x32_bf16 v[22:25], v[230:233], v[126:129], v[22:25]
	v_mfma_f32_16x16x32_bf16 v[18:21], v[242:245], v[126:129], v[18:21]
	v_mfma_f32_16x16x32_bf16 v[14:17], v[230:233], v[190:193], v[14:17]
	v_mfma_f32_16x16x32_bf16 v[10:13], v[242:245], v[190:193], v[10:13]
	v_mfma_f32_16x16x32_bf16 v[6:9], v[230:233], v[198:201], v[6:9]
	v_mfma_f32_16x16x32_bf16 v[2:5], v[242:245], v[198:201], v[2:5]
	s_add_i32 s54, 0, 0x18000
	v_add_u32_e32 v110, s54, v179
	s_barrier
	ds_read_b128 v[98:101], v110
	ds_read_b128 v[102:105], v110 offset:1024
	ds_read_b128 v[106:109], v110 offset:2048
	ds_read_b128 v[110:113], v110 offset:3072
	s_add_u32 s12, s48, 0x3e000
	s_addc_u32 s13, s49, 0
	s_mov_b32 m0, s89
	v_lshl_add_u64 v[226:227], s[12:13], 0, v[162:163]
	ds_read_b128 v[114:117], v184 offset:32768
	ds_read_b128 v[118:121], v184 offset:33792
	ds_read_b128 v[122:125], v184 offset:34816
	ds_read_b128 v[126:129], v184 offset:35840
	ds_read_b128 v[186:189], v184 offset:36864
	ds_read_b128 v[190:193], v184 offset:37888
	ds_read_b128 v[194:197], v184 offset:38912
	ds_read_b128 v[198:201], v184 offset:39936
	global_load_lds_dwordx4 v[226:227], off
	v_lshl_add_u64 v[226:227], s[12:13], 0, v[164:165]
	s_mov_b32 m0, s91
	s_nop 0
	global_load_lds_dwordx4 v[226:227], off
	s_waitcnt lgkmcnt(8)
	s_add_i32 s12, 0, 0x1c000
	s_add_i32 s13, s54, s78
	v_add_u32_e32 v242, s12, v179
	ds_read_b128 v[226:229], v242
	ds_read_b128 v[230:233], v242 offset:1024
	ds_read_b128 v[234:237], v242 offset:2048
	ds_read_b128 v[242:245], v242 offset:3072
	s_barrier
	s_waitcnt lgkmcnt(0)
	s_waitcnt lgkmcnt(0)
	v_mfma_f32_16x16x32_bf16 v[158:161], v[98:101], v[114:117], v[158:161]
	v_mfma_f32_16x16x32_bf16 v[154:157], v[106:109], v[114:117], v[154:157]
	v_mfma_f32_16x16x32_bf16 v[150:153], v[98:101], v[122:125], v[150:153]
	v_mfma_f32_16x16x32_bf16 v[146:149], v[106:109], v[122:125], v[146:149]
	v_mfma_f32_16x16x32_bf16 v[142:145], v[98:101], v[186:189], v[142:145]
	v_mfma_f32_16x16x32_bf16 v[138:141], v[106:109], v[186:189], v[138:141]
	v_mfma_f32_16x16x32_bf16 v[134:137], v[98:101], v[194:197], v[134:137]
	v_mfma_f32_16x16x32_bf16 v[130:133], v[106:109], v[194:197], v[130:133]
	v_mfma_f32_16x16x32_bf16 v[158:161], v[102:105], v[118:121], v[158:161]
	v_mfma_f32_16x16x32_bf16 v[154:157], v[110:113], v[118:121], v[154:157]
	v_mfma_f32_16x16x32_bf16 v[150:153], v[102:105], v[126:129], v[150:153]
	v_mfma_f32_16x16x32_bf16 v[146:149], v[110:113], v[126:129], v[146:149]
	v_mfma_f32_16x16x32_bf16 v[142:145], v[102:105], v[190:193], v[142:145]
	v_mfma_f32_16x16x32_bf16 v[138:141], v[110:113], v[190:193], v[138:141]
	v_mfma_f32_16x16x32_bf16 v[134:137], v[102:105], v[198:201], v[134:137]
	v_mfma_f32_16x16x32_bf16 v[130:133], v[110:113], v[198:201], v[130:133]
	s_waitcnt lgkmcnt(0)
	s_waitcnt lgkmcnt(0)
	v_mfma_f32_16x16x32_bf16 v[62:65], v[226:229], v[114:117], v[62:65]
	v_mfma_f32_16x16x32_bf16 v[58:61], v[234:237], v[114:117], v[58:61]
	v_mfma_f32_16x16x32_bf16 v[54:57], v[226:229], v[122:125], v[54:57]
	v_mfma_f32_16x16x32_bf16 v[50:53], v[234:237], v[122:125], v[50:53]
	v_mfma_f32_16x16x32_bf16 v[46:49], v[226:229], v[186:189], v[46:49]
	v_mfma_f32_16x16x32_bf16 v[42:45], v[234:237], v[186:189], v[42:45]
	v_mfma_f32_16x16x32_bf16 v[38:41], v[226:229], v[194:197], v[38:41]
	v_mfma_f32_16x16x32_bf16 v[34:37], v[234:237], v[194:197], v[34:37]
	v_mfma_f32_16x16x32_bf16 v[62:65], v[230:233], v[118:121], v[62:65]
	v_mfma_f32_16x16x32_bf16 v[58:61], v[242:245], v[118:121], v[58:61]
	v_mfma_f32_16x16x32_bf16 v[54:57], v[230:233], v[126:129], v[54:57]
	v_mfma_f32_16x16x32_bf16 v[50:53], v[242:245], v[126:129], v[50:53]
	v_mfma_f32_16x16x32_bf16 v[46:49], v[230:233], v[190:193], v[46:49]
	v_mfma_f32_16x16x32_bf16 v[42:45], v[242:245], v[190:193], v[42:45]
	v_mfma_f32_16x16x32_bf16 v[38:41], v[230:233], v[198:201], v[38:41]
	v_mfma_f32_16x16x32_bf16 v[34:37], v[242:245], v[198:201], v[34:37]
	s_mov_b32 m0, s79
	v_lshl_add_u64 v[174:175], v[248:249], 0, s[20:21]
	s_barrier
	ds_read_b128 v[114:117], v184 offset:49152
	ds_read_b128 v[118:121], v184 offset:50176
	ds_read_b128 v[122:125], v184 offset:51200
	ds_read_b128 v[126:129], v184 offset:52224
	ds_read_b128 v[186:189], v184 offset:53248
	ds_read_b128 v[190:193], v184 offset:54272
	ds_read_b128 v[194:197], v184 offset:55296
	ds_read_b128 v[198:201], v184 offset:56320
	global_load_lds_dwordx4 v[174:175], off
	v_lshl_add_u64 v[174:175], v[250:251], 0, s[20:21]
	s_mov_b32 m0, s87
	s_nop 0
	global_load_lds_dwordx4 v[174:175], off
	v_lshl_add_u64 v[174:175], s[2:3], 0, v[0:1]
	v_lshl_add_u64 v[174:175], v[174:175], 0, s[20:21]
	s_mov_b32 m0, s13
	s_nop 0
	global_load_lds_dwordx4 v[174:175], off
	v_lshl_add_u64 v[174:175], v[246:247], 0, s[20:21]
	s_add_i32 m0, s13, 0x2000
	s_nop 0
	global_load_lds_dwordx4 v[174:175], off
	s_add_u32 s2, s2, 0x40080
	s_addc_u32 s3, s3, 0
	s_add_i32 s12, s12, s78
	v_lshl_add_u64 v[174:175], s[2:3], 0, v[0:1]
	s_mov_b32 m0, s12
	s_nop 0
	global_load_lds_dwordx4 v[174:175], off
	v_lshl_add_u64 v[174:175], s[2:3], 0, v[166:167]
	s_add_i32 m0, s12, 0x2000
	s_nop 0
	global_load_lds_dwordx4 v[174:175], off
	s_waitcnt vmcnt(6)
	s_barrier
	s_waitcnt lgkmcnt(0)
	s_waitcnt lgkmcnt(0)
	v_mfma_f32_16x16x32_bf16 v[94:97], v[98:101], v[114:117], v[94:97]
	v_mfma_f32_16x16x32_bf16 v[90:93], v[106:109], v[114:117], v[90:93]
	v_mfma_f32_16x16x32_bf16 v[86:89], v[98:101], v[122:125], v[86:89]
	v_mfma_f32_16x16x32_bf16 v[82:85], v[106:109], v[122:125], v[82:85]
	v_mfma_f32_16x16x32_bf16 v[78:81], v[98:101], v[186:189], v[78:81]
	v_mfma_f32_16x16x32_bf16 v[74:77], v[106:109], v[186:189], v[74:77]
	v_mfma_f32_16x16x32_bf16 v[70:73], v[98:101], v[194:197], v[70:73]
	v_mfma_f32_16x16x32_bf16 v[66:69], v[106:109], v[194:197], v[66:69]
	v_mfma_f32_16x16x32_bf16 v[94:97], v[102:105], v[118:121], v[94:97]
	v_mfma_f32_16x16x32_bf16 v[90:93], v[110:113], v[118:121], v[90:93]
	v_mfma_f32_16x16x32_bf16 v[86:89], v[102:105], v[126:129], v[86:89]
	v_mfma_f32_16x16x32_bf16 v[82:85], v[110:113], v[126:129], v[82:85]
	v_mfma_f32_16x16x32_bf16 v[78:81], v[102:105], v[190:193], v[78:81]
	v_mfma_f32_16x16x32_bf16 v[74:77], v[110:113], v[190:193], v[74:77]
	v_mfma_f32_16x16x32_bf16 v[70:73], v[102:105], v[198:201], v[70:73]
	v_mfma_f32_16x16x32_bf16 v[66:69], v[110:113], v[198:201], v[66:69]
	v_mfma_f32_16x16x32_bf16 v[30:33], v[226:229], v[114:117], v[30:33]
	v_mfma_f32_16x16x32_bf16 v[26:29], v[234:237], v[114:117], v[26:29]
	v_mfma_f32_16x16x32_bf16 v[22:25], v[226:229], v[122:125], v[22:25]
	v_mfma_f32_16x16x32_bf16 v[18:21], v[234:237], v[122:125], v[18:21]
	v_mfma_f32_16x16x32_bf16 v[14:17], v[226:229], v[186:189], v[14:17]
	v_mfma_f32_16x16x32_bf16 v[10:13], v[234:237], v[186:189], v[10:13]
	v_mfma_f32_16x16x32_bf16 v[6:9], v[226:229], v[194:197], v[6:9]
	v_mfma_f32_16x16x32_bf16 v[2:5], v[234:237], v[194:197], v[2:5]
	v_mfma_f32_16x16x32_bf16 v[30:33], v[230:233], v[118:121], v[30:33]
	v_mfma_f32_16x16x32_bf16 v[26:29], v[242:245], v[118:121], v[26:29]
	v_mfma_f32_16x16x32_bf16 v[22:25], v[230:233], v[126:129], v[22:25]
	v_mfma_f32_16x16x32_bf16 v[18:21], v[242:245], v[126:129], v[18:21]
	v_mfma_f32_16x16x32_bf16 v[14:17], v[230:233], v[190:193], v[14:17]
	v_mfma_f32_16x16x32_bf16 v[10:13], v[242:245], v[190:193], v[10:13]
	v_mfma_f32_16x16x32_bf16 v[6:9], v[230:233], v[198:201], v[6:9]
	v_mfma_f32_16x16x32_bf16 v[2:5], v[242:245], v[198:201], v[2:5]
	s_add_i32 s53, s53, 2
	s_add_u32 s34, s34, 0x100
	s_addc_u32 s35, s35, 0
	s_add_u32 s51, s51, 0x100
	s_addc_u32 s52, s52, 0
	s_cmp_gt_u32 s53, 13
	s_barrier
	s_cbranch_scc0 .LBB0_104
.Lpeel_x_0:
	s_add_i32 s1, s50, 0xffffffbd
	s_cmpk_gt_i32 s50, 0x42
	s_cselect_b32 s1, s1, s50
	s_mul_i32 s23, s1, 0xf8
	s_cselect_b32 s2, 0x4000, 0
	s_cselect_b32 s3, 0x100, s37
	s_add_i32 s23, s23, s84
	v_add_u32_e32 v188, s88, v178
	s_mov_b32 s50, 0xbfb8aa3b
	s_mov_b32 s51, 0xbfb8aa3b
	ds_read_b128 v[126:129], v188
	ds_read_b128 v[122:125], v188 offset:128
	ds_read_b128 v[114:117], v188 offset:256
	ds_read_b128 v[118:121], v188 offset:384
	ds_read_b128 v[110:113], v188 offset:512
	ds_read_b128 v[106:109], v188 offset:640
	ds_read_b128 v[98:101], v188 offset:768
	ds_read_b128 v[102:105], v188 offset:896
	v_readlane_b32 s12, v252, 28
	v_readlane_b32 s13, v252, 29
	v_bfe_u32 v231, v202, 5, 1
	v_and_b32_e32 v174, 48, v180
	v_lshl_or_b32 v174, v231, 3, v174
	v_lshl_or_b32 v174, s0, 7, v174
	v_bfe_u32 v230, v202, 4, 1
	v_lshl_add_u32 v186, v177, 2, s23
	v_cmp_eq_u32_e32 vcc, 1, v230
	s_or_b64 s[52:53], s[42:43], vcc
	v_cmp_eq_u32_e32 vcc, 0, v230
	s_or_b64 s[54:55], s[44:45], vcc
	v_add_u32_e32 v186, v186, v230
	v_add_u32_e32 v187, s2, v186
	v_mul_u32_u24_e32 v187, 0x1600, v187
	v_lshl_add_u32 v187, v174, 1, v187
	s_waitcnt lgkmcnt(0)
	v_pk_fma_f32 v[190:191], v[158:159], v[122:123], v[118:119]
	v_pk_fma_f32 v[192:193], v[160:161], v[124:125], v[120:121]
	v_pk_fma_f32 v[194:195], v[154:155], v[106:107], v[102:103]
	v_pk_fma_f32 v[196:197], v[156:157], v[108:109], v[104:105]
	v_add_u32_e32 v230, 0, v186
	v_fmac_f32_dpp v190, v134, v126 row_ror:1 row_mask:0xf bank_mask:0xf
	v_fmac_f32_dpp v191, v135, v127 row_ror:1 row_mask:0xf bank_mask:0xf
	v_fmac_f32_dpp v192, v136, v128 row_ror:1 row_mask:0xf bank_mask:0xf
	v_fmac_f32_dpp v193, v137, v129 row_ror:1 row_mask:0xf bank_mask:0xf
	v_fmac_f32_dpp v194, v130, v110 row_ror:1 row_mask:0xf bank_mask:0xf
	v_fmac_f32_dpp v195, v131, v111 row_ror:1 row_mask:0xf bank_mask:0xf
	v_fmac_f32_dpp v196, v132, v112 row_ror:1 row_mask:0xf bank_mask:0xf
	v_fmac_f32_dpp v197, v133, v113 row_ror:1 row_mask:0xf bank_mask:0xf
	v_pk_fma_f32 v[190:191], v[150:151], v[114:115], v[190:191]
	v_pk_fma_f32 v[192:193], v[152:153], v[116:117], v[192:193]
	v_pk_fma_f32 v[194:195], v[146:147], v[98:99], v[194:195]
	v_pk_fma_f32 v[196:197], v[148:149], v[100:101], v[196:197]
	v_pk_mul_f32 v[198:199], v[190:191], s[50:51]
	v_pk_mul_f32 v[200:201], v[192:193], s[50:51]
	v_exp_f32_e32 v198, v198
	v_exp_f32_e32 v199, v199
	v_exp_f32_e32 v200, v200
	v_exp_f32_e32 v201, v201
	v_add_f32_e32 v198, 1.0, v198
	v_add_f32_e32 v199, 1.0, v199
	v_add_f32_e32 v200, 1.0, v200
	v_add_f32_e32 v201, 1.0, v201
	v_rcp_f32_e32 v198, v198
	v_rcp_f32_e32 v199, v199
	v_rcp_f32_e32 v200, v200
	v_rcp_f32_e32 v201, v201
	v_pk_mul_f32 v[190:191], v[190:191], v[198:199]
	v_pk_mul_f32 v[192:193], v[192:193], v[200:201]
	v_pk_mul_f32 v[190:191], v[190:191], v[194:195]
	v_pk_mul_f32 v[192:193], v[192:193], v[196:197]
	v_cvt_pk_bf16_f32 v232, v190, v191
	v_cvt_pk_bf16_f32 v233, v192, v193
	v_pk_fma_f32 v[190:191], v[150:151], v[122:123], v[118:119]
	v_pk_fma_f32 v[192:193], v[152:153], v[124:125], v[120:121]
	v_pk_fma_f32 v[194:195], v[146:147], v[106:107], v[102:103]
	v_pk_fma_f32 v[196:197], v[148:149], v[108:109], v[104:105]
	v_pk_fma_f32 v[190:191], v[158:159], v[126:127], v[190:191]
	v_pk_fma_f32 v[192:193], v[160:161], v[128:129], v[192:193]
	v_pk_fma_f32 v[194:195], v[154:155], v[110:111], v[194:195]
	v_pk_fma_f32 v[196:197], v[156:157], v[112:113], v[196:197]
	v_pk_fma_f32 v[190:191], v[142:143], v[114:115], v[190:191]
	v_pk_fma_f32 v[192:193], v[144:145], v[116:117], v[192:193]
	v_pk_fma_f32 v[194:195], v[138:139], v[98:99], v[194:195]
	v_pk_fma_f32 v[196:197], v[140:141], v[100:101], v[196:197]
	v_pk_mul_f32 v[198:199], v[190:191], s[50:51]
	v_pk_mul_f32 v[200:201], v[192:193], s[50:51]
	v_exp_f32_e32 v198, v198
	v_exp_f32_e32 v199, v199
	v_exp_f32_e32 v200, v200
	v_exp_f32_e32 v201, v201
	v_add_f32_e32 v198, 1.0, v198
	v_add_f32_e32 v199, 1.0, v199
	v_add_f32_e32 v200, 1.0, v200
	v_add_f32_e32 v201, 1.0, v201
	v_rcp_f32_e32 v198, v198
	v_rcp_f32_e32 v199, v199
	v_rcp_f32_e32 v200, v200
	v_rcp_f32_e32 v201, v201
	v_pk_mul_f32 v[190:191], v[190:191], v[198:199]
	v_pk_mul_f32 v[192:193], v[192:193], v[200:201]
	v_pk_mul_f32 v[190:191], v[190:191], v[194:195]
	v_pk_mul_f32 v[192:193], v[192:193], v[196:197]
	v_cvt_pk_bf16_f32 v234, v190, v191
	v_cvt_pk_bf16_f32 v235, v192, v193
	v_cmp_gt_i32_e32 vcc, s3, v230
	s_and_b64 vcc, vcc, s[52:53]
	s_nop 0
	v_permlane16_swap_b32_e32 v232, v234
	v_permlane16_swap_b32_e32 v233, v235
	s_and_saveexec_b64 s[0:1], vcc
	global_store_dwordx4 v187, v[232:235], s[12:13]
	s_mov_b64 exec, s[0:1]
	v_pk_fma_f32 v[190:191], v[142:143], v[122:123], v[118:119]
	v_pk_fma_f32 v[192:193], v[144:145], v[124:125], v[120:121]
	v_pk_fma_f32 v[194:195], v[138:139], v[106:107], v[102:103]
	v_pk_fma_f32 v[196:197], v[140:141], v[108:109], v[104:105]
	v_add_u32_e32 v230, 2, v186
	v_add_u32_e32 v231, 0x2c00, v187
	v_pk_fma_f32 v[190:191], v[150:151], v[126:127], v[190:191]
	v_pk_fma_f32 v[192:193], v[152:153], v[128:129], v[192:193]
	v_pk_fma_f32 v[194:195], v[146:147], v[110:111], v[194:195]
	v_pk_fma_f32 v[196:197], v[148:149], v[112:113], v[196:197]
	v_pk_fma_f32 v[190:191], v[134:135], v[114:115], v[190:191]
	v_pk_fma_f32 v[192:193], v[136:137], v[116:117], v[192:193]
	v_pk_fma_f32 v[194:195], v[130:131], v[98:99], v[194:195]
	v_pk_fma_f32 v[196:197], v[132:133], v[100:101], v[196:197]
	v_pk_mul_f32 v[198:199], v[190:191], s[50:51]
	v_pk_mul_f32 v[200:201], v[192:193], s[50:51]
	v_exp_f32_e32 v198, v198
	v_exp_f32_e32 v199, v199
	v_exp_f32_e32 v200, v200
	v_exp_f32_e32 v201, v201
	v_add_f32_e32 v198, 1.0, v198
	v_add_f32_e32 v199, 1.0, v199
	v_add_f32_e32 v200, 1.0, v200
	v_add_f32_e32 v201, 1.0, v201
	v_rcp_f32_e32 v198, v198
	v_rcp_f32_e32 v199, v199
	v_rcp_f32_e32 v200, v200
	v_rcp_f32_e32 v201, v201
	v_pk_mul_f32 v[190:191], v[190:191], v[198:199]
	v_pk_mul_f32 v[192:193], v[192:193], v[200:201]
	v_pk_mul_f32 v[190:191], v[190:191], v[194:195]
	v_pk_mul_f32 v[192:193], v[192:193], v[196:197]
	v_cvt_pk_bf16_f32 v232, v190, v191
	v_cvt_pk_bf16_f32 v233, v192, v193
	v_pk_fma_f32 v[190:191], v[134:135], v[122:123], v[118:119]
	v_pk_fma_f32 v[192:193], v[136:137], v[124:125], v[120:121]
	v_pk_fma_f32 v[194:195], v[130:131], v[106:107], v[102:103]
	v_pk_fma_f32 v[196:197], v[132:133], v[108:109], v[104:105]
	v_pk_fma_f32 v[190:191], v[142:143], v[126:127], v[190:191]
	v_pk_fma_f32 v[192:193], v[144:145], v[128:129], v[192:193]
	v_pk_fma_f32 v[194:195], v[138:139], v[110:111], v[194:195]
	v_pk_fma_f32 v[196:197], v[140:141], v[112:113], v[196:197]
	v_fmac_f32_dpp v190, v158, v114 row_ror:15 row_mask:0xf bank_mask:0xf
	v_fmac_f32_dpp v191, v159, v115 row_ror:15 row_mask:0xf bank_mask:0xf
	v_fmac_f32_dpp v192, v160, v116 row_ror:15 row_mask:0xf bank_mask:0xf
	v_fmac_f32_dpp v193, v161, v117 row_ror:15 row_mask:0xf bank_mask:0xf
	v_fmac_f32_dpp v194, v154, v98 row_ror:15 row_mask:0xf bank_mask:0xf
	v_fmac_f32_dpp v195, v155, v99 row_ror:15 row_mask:0xf bank_mask:0xf
	v_fmac_f32_dpp v196, v156, v100 row_ror:15 row_mask:0xf bank_mask:0xf
	v_fmac_f32_dpp v197, v157, v101 row_ror:15 row_mask:0xf bank_mask:0xf
	v_pk_mul_f32 v[198:199], v[190:191], s[50:51]
	v_pk_mul_f32 v[200:201], v[192:193], s[50:51]
	v_exp_f32_e32 v198, v198
	v_exp_f32_e32 v199, v199
	v_exp_f32_e32 v200, v200
	v_exp_f32_e32 v201, v201
	v_add_f32_e32 v198, 1.0, v198
	v_add_f32_e32 v199, 1.0, v199
	v_add_f32_e32 v200, 1.0, v200
	v_add_f32_e32 v201, 1.0, v201
	v_rcp_f32_e32 v198, v198
	v_rcp_f32_e32 v199, v199
	v_rcp_f32_e32 v200, v200
	v_rcp_f32_e32 v201, v201
	v_pk_mul_f32 v[190:191], v[190:191], v[198:199]
	v_pk_mul_f32 v[192:193], v[192:193], v[200:201]
	v_pk_mul_f32 v[190:191], v[190:191], v[194:195]
	v_pk_mul_f32 v[192:193], v[192:193], v[196:197]
	v_cvt_pk_bf16_f32 v234, v190, v191
	v_cvt_pk_bf16_f32 v235, v192, v193
	v_cmp_gt_i32_e32 vcc, s3, v230
	s_and_b64 vcc, vcc, s[54:55]
	s_nop 0
	v_permlane16_swap_b32_e32 v232, v234
	v_permlane16_swap_b32_e32 v233, v235
	s_and_saveexec_b64 s[0:1], vcc
	global_store_dwordx4 v231, v[232:235], s[12:13]
	s_mov_b64 exec, s[0:1]
	ds_read_b128 v[130:133], v188 offset:64
	ds_read_b128 v[134:137], v188 offset:192
	ds_read_b128 v[138:141], v188 offset:320
	ds_read_b128 v[142:145], v188 offset:448
	ds_read_b128 v[146:149], v188 offset:576
	ds_read_b128 v[150:153], v188 offset:704
	ds_read_b128 v[154:157], v188 offset:832
	ds_read_b128 v[158:161], v188 offset:960
	v_pk_fma_f32 v[190:191], v[94:95], v[122:123], v[118:119]
	v_pk_fma_f32 v[192:193], v[96:97], v[124:125], v[120:121]
	v_pk_fma_f32 v[194:195], v[90:91], v[106:107], v[102:103]
	v_pk_fma_f32 v[196:197], v[92:93], v[108:109], v[104:105]
	v_add_u32_e32 v230, 0x7c, v186
	v_add_u32_e32 v231, 0xaa800, v187
	v_fmac_f32_dpp v190, v70, v126 row_ror:1 row_mask:0xf bank_mask:0xf
	v_fmac_f32_dpp v191, v71, v127 row_ror:1 row_mask:0xf bank_mask:0xf
	v_fmac_f32_dpp v192, v72, v128 row_ror:1 row_mask:0xf bank_mask:0xf
	v_fmac_f32_dpp v193, v73, v129 row_ror:1 row_mask:0xf bank_mask:0xf
	v_fmac_f32_dpp v194, v66, v110 row_ror:1 row_mask:0xf bank_mask:0xf
	v_fmac_f32_dpp v195, v67, v111 row_ror:1 row_mask:0xf bank_mask:0xf
	v_fmac_f32_dpp v196, v68, v112 row_ror:1 row_mask:0xf bank_mask:0xf
	v_fmac_f32_dpp v197, v69, v113 row_ror:1 row_mask:0xf bank_mask:0xf
	v_pk_fma_f32 v[190:191], v[86:87], v[114:115], v[190:191]
	v_pk_fma_f32 v[192:193], v[88:89], v[116:117], v[192:193]
	v_pk_fma_f32 v[194:195], v[82:83], v[98:99], v[194:195]
	v_pk_fma_f32 v[196:197], v[84:85], v[100:101], v[196:197]
	v_pk_mul_f32 v[198:199], v[190:191], s[50:51]
	v_pk_mul_f32 v[200:201], v[192:193], s[50:51]
	v_exp_f32_e32 v198, v198
	v_exp_f32_e32 v199, v199
	v_exp_f32_e32 v200, v200
	v_exp_f32_e32 v201, v201
	v_add_f32_e32 v198, 1.0, v198
	v_add_f32_e32 v199, 1.0, v199
	v_add_f32_e32 v200, 1.0, v200
	v_add_f32_e32 v201, 1.0, v201
	v_rcp_f32_e32 v198, v198
	v_rcp_f32_e32 v199, v199
	v_rcp_f32_e32 v200, v200
	v_rcp_f32_e32 v201, v201
	v_pk_mul_f32 v[190:191], v[190:191], v[198:199]
	v_pk_mul_f32 v[192:193], v[192:193], v[200:201]
	v_pk_mul_f32 v[190:191], v[190:191], v[194:195]
	v_pk_mul_f32 v[192:193], v[192:193], v[196:197]
	v_cvt_pk_bf16_f32 v232, v190, v191
	v_cvt_pk_bf16_f32 v233, v192, v193
	v_pk_fma_f32 v[190:191], v[86:87], v[122:123], v[118:119]
	v_pk_fma_f32 v[192:193], v[88:89], v[124:125], v[120:121]
	v_pk_fma_f32 v[194:195], v[82:83], v[106:107], v[102:103]
	v_pk_fma_f32 v[196:197], v[84:85], v[108:109], v[104:105]
	v_pk_fma_f32 v[190:191], v[94:95], v[126:127], v[190:191]
	v_pk_fma_f32 v[192:193], v[96:97], v[128:129], v[192:193]
	v_pk_fma_f32 v[194:195], v[90:91], v[110:111], v[194:195]
	v_pk_fma_f32 v[196:197], v[92:93], v[112:113], v[196:197]
	v_pk_fma_f32 v[190:191], v[78:79], v[114:115], v[190:191]
	v_pk_fma_f32 v[192:193], v[80:81], v[116:117], v[192:193]
	v_pk_fma_f32 v[194:195], v[74:75], v[98:99], v[194:195]
	v_pk_fma_f32 v[196:197], v[76:77], v[100:101], v[196:197]
	v_pk_mul_f32 v[198:199], v[190:191], s[50:51]
	v_pk_mul_f32 v[200:201], v[192:193], s[50:51]
	v_exp_f32_e32 v198, v198
	v_exp_f32_e32 v199, v199
	v_exp_f32_e32 v200, v200
	v_exp_f32_e32 v201, v201
	v_add_f32_e32 v198, 1.0, v198
	v_add_f32_e32 v199, 1.0, v199
	v_add_f32_e32 v200, 1.0, v200
	v_add_f32_e32 v201, 1.0, v201
	v_rcp_f32_e32 v198, v198
	v_rcp_f32_e32 v199, v199
	v_rcp_f32_e32 v200, v200
	v_rcp_f32_e32 v201, v201
	v_pk_mul_f32 v[190:191], v[190:191], v[198:199]
	v_pk_mul_f32 v[192:193], v[192:193], v[200:201]
	v_pk_mul_f32 v[190:191], v[190:191], v[194:195]
	v_pk_mul_f32 v[192:193], v[192:193], v[196:197]
	v_cvt_pk_bf16_f32 v234, v190, v191
	v_cvt_pk_bf16_f32 v235, v192, v193
	v_cmp_gt_i32_e32 vcc, s3, v230
	s_and_b64 vcc, vcc, s[52:53]
	s_nop 0
	v_permlane16_swap_b32_e32 v232, v234
	v_permlane16_swap_b32_e32 v233, v235
	s_and_saveexec_b64 s[0:1], vcc
	global_store_dwordx4 v231, v[232:235], s[12:13]
	s_mov_b64 exec, s[0:1]
	v_pk_fma_f32 v[190:191], v[78:79], v[122:123], v[118:119]
	v_pk_fma_f32 v[192:193], v[80:81], v[124:125], v[120:121]
	v_pk_fma_f32 v[194:195], v[74:75], v[106:107], v[102:103]
	v_pk_fma_f32 v[196:197], v[76:77], v[108:109], v[104:105]
	v_add_u32_e32 v230, 0x7e, v186
	v_add_u32_e32 v231, 0xad400, v187
	v_pk_fma_f32 v[190:191], v[86:87], v[126:127], v[190:191]
	v_pk_fma_f32 v[192:193], v[88:89], v[128:129], v[192:193]
	v_pk_fma_f32 v[194:195], v[82:83], v[110:111], v[194:195]
	v_pk_fma_f32 v[196:197], v[84:85], v[112:113], v[196:197]
	v_pk_fma_f32 v[190:191], v[70:71], v[114:115], v[190:191]
	v_pk_fma_f32 v[192:193], v[72:73], v[116:117], v[192:193]
	v_pk_fma_f32 v[194:195], v[66:67], v[98:99], v[194:195]
	v_pk_fma_f32 v[196:197], v[68:69], v[100:101], v[196:197]
	v_pk_mul_f32 v[198:199], v[190:191], s[50:51]
	v_pk_mul_f32 v[200:201], v[192:193], s[50:51]
	v_exp_f32_e32 v198, v198
	v_exp_f32_e32 v199, v199
	v_exp_f32_e32 v200, v200
	v_exp_f32_e32 v201, v201
	v_add_f32_e32 v198, 1.0, v198
	v_add_f32_e32 v199, 1.0, v199
	v_add_f32_e32 v200, 1.0, v200
	v_add_f32_e32 v201, 1.0, v201
	v_rcp_f32_e32 v198, v198
	v_rcp_f32_e32 v199, v199
	v_rcp_f32_e32 v200, v200
	v_rcp_f32_e32 v201, v201
	v_pk_mul_f32 v[190:191], v[190:191], v[198:199]
	v_pk_mul_f32 v[192:193], v[192:193], v[200:201]
	v_pk_mul_f32 v[190:191], v[190:191], v[194:195]
	v_pk_mul_f32 v[192:193], v[192:193], v[196:197]
	v_cvt_pk_bf16_f32 v232, v190, v191
	v_cvt_pk_bf16_f32 v233, v192, v193
	v_pk_fma_f32 v[190:191], v[70:71], v[122:123], v[118:119]
	v_pk_fma_f32 v[192:193], v[72:73], v[124:125], v[120:121]
	v_pk_fma_f32 v[194:195], v[66:67], v[106:107], v[102:103]
	v_pk_fma_f32 v[196:197], v[68:69], v[108:109], v[104:105]
	v_pk_fma_f32 v[190:191], v[78:79], v[126:127], v[190:191]
	v_pk_fma_f32 v[192:193], v[80:81], v[128:129], v[192:193]
	v_pk_fma_f32 v[194:195], v[74:75], v[110:111], v[194:195]
	v_pk_fma_f32 v[196:197], v[76:77], v[112:113], v[196:197]
	v_fmac_f32_dpp v190, v94, v114 row_ror:15 row_mask:0xf bank_mask:0xf
	v_fmac_f32_dpp v191, v95, v115 row_ror:15 row_mask:0xf bank_mask:0xf
	v_fmac_f32_dpp v192, v96, v116 row_ror:15 row_mask:0xf bank_mask:0xf
	v_fmac_f32_dpp v193, v97, v117 row_ror:15 row_mask:0xf bank_mask:0xf
	v_fmac_f32_dpp v194, v90, v98 row_ror:15 row_mask:0xf bank_mask:0xf
	v_fmac_f32_dpp v195, v91, v99 row_ror:15 row_mask:0xf bank_mask:0xf
	v_fmac_f32_dpp v196, v92, v100 row_ror:15 row_mask:0xf bank_mask:0xf
	v_fmac_f32_dpp v197, v93, v101 row_ror:15 row_mask:0xf bank_mask:0xf
	v_pk_mul_f32 v[198:199], v[190:191], s[50:51]
	v_pk_mul_f32 v[200:201], v[192:193], s[50:51]
	v_exp_f32_e32 v198, v198
	v_exp_f32_e32 v199, v199
	v_exp_f32_e32 v200, v200
	v_exp_f32_e32 v201, v201
	v_add_f32_e32 v198, 1.0, v198
	v_add_f32_e32 v199, 1.0, v199
	v_add_f32_e32 v200, 1.0, v200
	v_add_f32_e32 v201, 1.0, v201
	v_rcp_f32_e32 v198, v198
	v_rcp_f32_e32 v199, v199
	v_rcp_f32_e32 v200, v200
	v_rcp_f32_e32 v201, v201
	v_pk_mul_f32 v[190:191], v[190:191], v[198:199]
	v_pk_mul_f32 v[192:193], v[192:193], v[200:201]
	v_pk_mul_f32 v[190:191], v[190:191], v[194:195]
	v_pk_mul_f32 v[192:193], v[192:193], v[196:197]
	v_cvt_pk_bf16_f32 v234, v190, v191
	v_cvt_pk_bf16_f32 v235, v192, v193
	v_cmp_gt_i32_e32 vcc, s3, v230
	s_and_b64 vcc, vcc, s[54:55]
	s_nop 0
	v_permlane16_swap_b32_e32 v232, v234
	v_permlane16_swap_b32_e32 v233, v235
	s_and_saveexec_b64 s[0:1], vcc
	global_store_dwordx4 v231, v[232:235], s[12:13]
	s_mov_b64 exec, s[0:1]
	s_waitcnt lgkmcnt(0)
	v_pk_fma_f32 v[190:191], v[62:63], v[134:135], v[142:143]
	v_pk_fma_f32 v[192:193], v[64:65], v[136:137], v[144:145]
	v_pk_fma_f32 v[194:195], v[58:59], v[150:151], v[158:159]
	v_pk_fma_f32 v[196:197], v[60:61], v[152:153], v[160:161]
	v_add_u32_e32 v230, 0, v186
	v_fmac_f32_dpp v190, v38, v130 row_ror:1 row_mask:0xf bank_mask:0xf
	v_fmac_f32_dpp v191, v39, v131 row_ror:1 row_mask:0xf bank_mask:0xf
	v_fmac_f32_dpp v192, v40, v132 row_ror:1 row_mask:0xf bank_mask:0xf
	v_fmac_f32_dpp v193, v41, v133 row_ror:1 row_mask:0xf bank_mask:0xf
	v_fmac_f32_dpp v194, v34, v146 row_ror:1 row_mask:0xf bank_mask:0xf
	v_fmac_f32_dpp v195, v35, v147 row_ror:1 row_mask:0xf bank_mask:0xf
	v_fmac_f32_dpp v196, v36, v148 row_ror:1 row_mask:0xf bank_mask:0xf
	v_fmac_f32_dpp v197, v37, v149 row_ror:1 row_mask:0xf bank_mask:0xf
	v_pk_fma_f32 v[190:191], v[54:55], v[138:139], v[190:191]
	v_pk_fma_f32 v[192:193], v[56:57], v[140:141], v[192:193]
	v_pk_fma_f32 v[194:195], v[50:51], v[154:155], v[194:195]
	v_pk_fma_f32 v[196:197], v[52:53], v[156:157], v[196:197]
	v_pk_mul_f32 v[198:199], v[190:191], s[50:51]
	v_pk_mul_f32 v[200:201], v[192:193], s[50:51]
	v_exp_f32_e32 v198, v198
	v_exp_f32_e32 v199, v199
	v_exp_f32_e32 v200, v200
	v_exp_f32_e32 v201, v201
	v_add_f32_e32 v198, 1.0, v198
	v_add_f32_e32 v199, 1.0, v199
	v_add_f32_e32 v200, 1.0, v200
	v_add_f32_e32 v201, 1.0, v201
	v_rcp_f32_e32 v198, v198
	v_rcp_f32_e32 v199, v199
	v_rcp_f32_e32 v200, v200
	v_rcp_f32_e32 v201, v201
	v_pk_mul_f32 v[190:191], v[190:191], v[198:199]
	v_pk_mul_f32 v[192:193], v[192:193], v[200:201]
	v_pk_mul_f32 v[190:191], v[190:191], v[194:195]
	v_pk_mul_f32 v[192:193], v[192:193], v[196:197]
	v_cvt_pk_bf16_f32 v232, v190, v191
	v_cvt_pk_bf16_f32 v233, v192, v193
	v_pk_fma_f32 v[190:191], v[54:55], v[134:135], v[142:143]
	v_pk_fma_f32 v[192:193], v[56:57], v[136:137], v[144:145]
	v_pk_fma_f32 v[194:195], v[50:51], v[150:151], v[158:159]
	v_pk_fma_f32 v[196:197], v[52:53], v[152:153], v[160:161]
	v_pk_fma_f32 v[190:191], v[62:63], v[130:131], v[190:191]
	v_pk_fma_f32 v[192:193], v[64:65], v[132:133], v[192:193]
	v_pk_fma_f32 v[194:195], v[58:59], v[146:147], v[194:195]
	v_pk_fma_f32 v[196:197], v[60:61], v[148:149], v[196:197]
	v_pk_fma_f32 v[190:191], v[46:47], v[138:139], v[190:191]
	v_pk_fma_f32 v[192:193], v[48:49], v[140:141], v[192:193]
	v_pk_fma_f32 v[194:195], v[42:43], v[154:155], v[194:195]
	v_pk_fma_f32 v[196:197], v[44:45], v[156:157], v[196:197]
	v_pk_mul_f32 v[198:199], v[190:191], s[50:51]
	v_pk_mul_f32 v[200:201], v[192:193], s[50:51]
	v_exp_f32_e32 v198, v198
	v_exp_f32_e32 v199, v199
	v_exp_f32_e32 v200, v200
	v_exp_f32_e32 v201, v201
	v_add_f32_e32 v198, 1.0, v198
	v_add_f32_e32 v199, 1.0, v199
	v_add_f32_e32 v200, 1.0, v200
	v_add_f32_e32 v201, 1.0, v201
	v_rcp_f32_e32 v198, v198
	v_rcp_f32_e32 v199, v199
	v_rcp_f32_e32 v200, v200
	v_rcp_f32_e32 v201, v201
	v_pk_mul_f32 v[190:191], v[190:191], v[198:199]
	v_pk_mul_f32 v[192:193], v[192:193], v[200:201]
	v_pk_mul_f32 v[190:191], v[190:191], v[194:195]
	v_pk_mul_f32 v[192:193], v[192:193], v[196:197]
	v_cvt_pk_bf16_f32 v234, v190, v191
	v_cvt_pk_bf16_f32 v235, v192, v193
	v_cmp_gt_i32_e32 vcc, s3, v230
	s_and_b64 vcc, vcc, s[52:53]
	s_nop 0
	v_permlane16_swap_b32_e32 v232, v234
	v_permlane16_swap_b32_e32 v233, v235
	s_and_saveexec_b64 s[0:1], vcc
	global_store_dwordx4 v187, v[232:235], s[12:13] offset:128
	s_mov_b64 exec, s[0:1]
	v_pk_fma_f32 v[190:191], v[46:47], v[134:135], v[142:143]
	v_pk_fma_f32 v[192:193], v[48:49], v[136:137], v[144:145]
	v_pk_fma_f32 v[194:195], v[42:43], v[150:151], v[158:159]
	v_pk_fma_f32 v[196:197], v[44:45], v[152:153], v[160:161]
	v_add_u32_e32 v230, 2, v186
	v_add_u32_e32 v231, 0x2c00, v187
	v_pk_fma_f32 v[190:191], v[54:55], v[130:131], v[190:191]
	v_pk_fma_f32 v[192:193], v[56:57], v[132:133], v[192:193]
	v_pk_fma_f32 v[194:195], v[50:51], v[146:147], v[194:195]
	v_pk_fma_f32 v[196:197], v[52:53], v[148:149], v[196:197]
	v_pk_fma_f32 v[190:191], v[38:39], v[138:139], v[190:191]
	v_pk_fma_f32 v[192:193], v[40:41], v[140:141], v[192:193]
	v_pk_fma_f32 v[194:195], v[34:35], v[154:155], v[194:195]
	v_pk_fma_f32 v[196:197], v[36:37], v[156:157], v[196:197]
	v_pk_mul_f32 v[198:199], v[190:191], s[50:51]
	v_pk_mul_f32 v[200:201], v[192:193], s[50:51]
	v_exp_f32_e32 v198, v198
	v_exp_f32_e32 v199, v199
	v_exp_f32_e32 v200, v200
	v_exp_f32_e32 v201, v201
	v_add_f32_e32 v198, 1.0, v198
	v_add_f32_e32 v199, 1.0, v199
	v_add_f32_e32 v200, 1.0, v200
	v_add_f32_e32 v201, 1.0, v201
	v_rcp_f32_e32 v198, v198
	v_rcp_f32_e32 v199, v199
	v_rcp_f32_e32 v200, v200
	v_rcp_f32_e32 v201, v201
	v_pk_mul_f32 v[190:191], v[190:191], v[198:199]
	v_pk_mul_f32 v[192:193], v[192:193], v[200:201]
	v_pk_mul_f32 v[190:191], v[190:191], v[194:195]
	v_pk_mul_f32 v[192:193], v[192:193], v[196:197]
	v_cvt_pk_bf16_f32 v232, v190, v191
	v_cvt_pk_bf16_f32 v233, v192, v193
	v_pk_fma_f32 v[190:191], v[38:39], v[134:135], v[142:143]
	v_pk_fma_f32 v[192:193], v[40:41], v[136:137], v[144:145]
	v_pk_fma_f32 v[194:195], v[34:35], v[150:151], v[158:159]
	v_pk_fma_f32 v[196:197], v[36:37], v[152:153], v[160:161]
	v_pk_fma_f32 v[190:191], v[46:47], v[130:131], v[190:191]
	v_pk_fma_f32 v[192:193], v[48:49], v[132:133], v[192:193]
	v_pk_fma_f32 v[194:195], v[42:43], v[146:147], v[194:195]
	v_pk_fma_f32 v[196:197], v[44:45], v[148:149], v[196:197]
	v_fmac_f32_dpp v190, v62, v138 row_ror:15 row_mask:0xf bank_mask:0xf
	v_fmac_f32_dpp v191, v63, v139 row_ror:15 row_mask:0xf bank_mask:0xf
	v_fmac_f32_dpp v192, v64, v140 row_ror:15 row_mask:0xf bank_mask:0xf
	v_fmac_f32_dpp v193, v65, v141 row_ror:15 row_mask:0xf bank_mask:0xf
	v_fmac_f32_dpp v194, v58, v154 row_ror:15 row_mask:0xf bank_mask:0xf
	v_fmac_f32_dpp v195, v59, v155 row_ror:15 row_mask:0xf bank_mask:0xf
	v_fmac_f32_dpp v196, v60, v156 row_ror:15 row_mask:0xf bank_mask:0xf
	v_fmac_f32_dpp v197, v61, v157 row_ror:15 row_mask:0xf bank_mask:0xf
	v_pk_mul_f32 v[198:199], v[190:191], s[50:51]
	v_pk_mul_f32 v[200:201], v[192:193], s[50:51]
	v_exp_f32_e32 v198, v198
	v_exp_f32_e32 v199, v199
	v_exp_f32_e32 v200, v200
	v_exp_f32_e32 v201, v201
	v_add_f32_e32 v198, 1.0, v198
	v_add_f32_e32 v199, 1.0, v199
	v_add_f32_e32 v200, 1.0, v200
	v_add_f32_e32 v201, 1.0, v201
	v_rcp_f32_e32 v198, v198
	v_rcp_f32_e32 v199, v199
	v_rcp_f32_e32 v200, v200
	v_rcp_f32_e32 v201, v201
	v_pk_mul_f32 v[190:191], v[190:191], v[198:199]
	v_pk_mul_f32 v[192:193], v[192:193], v[200:201]
	v_pk_mul_f32 v[190:191], v[190:191], v[194:195]
	v_pk_mul_f32 v[192:193], v[192:193], v[196:197]
	v_cvt_pk_bf16_f32 v234, v190, v191
	v_cvt_pk_bf16_f32 v235, v192, v193
	v_cmp_gt_i32_e32 vcc, s3, v230
	s_and_b64 vcc, vcc, s[54:55]
	s_nop 0
	v_permlane16_swap_b32_e32 v232, v234
	v_permlane16_swap_b32_e32 v233, v235
	s_and_saveexec_b64 s[0:1], vcc
	global_store_dwordx4 v231, v[232:235], s[12:13] offset:128
	s_mov_b64 exec, s[0:1]
	v_pk_fma_f32 v[190:191], v[30:31], v[134:135], v[142:143]
	v_pk_fma_f32 v[192:193], v[32:33], v[136:137], v[144:145]
	v_pk_fma_f32 v[194:195], v[26:27], v[150:151], v[158:159]
	v_pk_fma_f32 v[196:197], v[28:29], v[152:153], v[160:161]
	v_add_u32_e32 v230, 0x7c, v186
	v_add_u32_e32 v231, 0xaa800, v187
	v_fmac_f32_dpp v190, v6, v130 row_ror:1 row_mask:0xf bank_mask:0xf
	v_fmac_f32_dpp v191, v7, v131 row_ror:1 row_mask:0xf bank_mask:0xf
	v_fmac_f32_dpp v192, v8, v132 row_ror:1 row_mask:0xf bank_mask:0xf
	v_fmac_f32_dpp v193, v9, v133 row_ror:1 row_mask:0xf bank_mask:0xf
	v_fmac_f32_dpp v194, v2, v146 row_ror:1 row_mask:0xf bank_mask:0xf
	v_fmac_f32_dpp v195, v3, v147 row_ror:1 row_mask:0xf bank_mask:0xf
	v_fmac_f32_dpp v196, v4, v148 row_ror:1 row_mask:0xf bank_mask:0xf
	v_fmac_f32_dpp v197, v5, v149 row_ror:1 row_mask:0xf bank_mask:0xf
	v_pk_fma_f32 v[190:191], v[22:23], v[138:139], v[190:191]
	v_pk_fma_f32 v[192:193], v[24:25], v[140:141], v[192:193]
	v_pk_fma_f32 v[194:195], v[18:19], v[154:155], v[194:195]
	v_pk_fma_f32 v[196:197], v[20:21], v[156:157], v[196:197]
	v_pk_mul_f32 v[198:199], v[190:191], s[50:51]
	v_pk_mul_f32 v[200:201], v[192:193], s[50:51]
	v_exp_f32_e32 v198, v198
	v_exp_f32_e32 v199, v199
	v_exp_f32_e32 v200, v200
	v_exp_f32_e32 v201, v201
	v_add_f32_e32 v198, 1.0, v198
	v_add_f32_e32 v199, 1.0, v199
	v_add_f32_e32 v200, 1.0, v200
	v_add_f32_e32 v201, 1.0, v201
	v_rcp_f32_e32 v198, v198
	v_rcp_f32_e32 v199, v199
	v_rcp_f32_e32 v200, v200
	v_rcp_f32_e32 v201, v201
	v_pk_mul_f32 v[190:191], v[190:191], v[198:199]
	v_pk_mul_f32 v[192:193], v[192:193], v[200:201]
	v_pk_mul_f32 v[190:191], v[190:191], v[194:195]
	v_pk_mul_f32 v[192:193], v[192:193], v[196:197]
	v_cvt_pk_bf16_f32 v232, v190, v191
	v_cvt_pk_bf16_f32 v233, v192, v193
	v_pk_fma_f32 v[190:191], v[22:23], v[134:135], v[142:143]
	v_pk_fma_f32 v[192:193], v[24:25], v[136:137], v[144:145]
	v_pk_fma_f32 v[194:195], v[18:19], v[150:151], v[158:159]
	v_pk_fma_f32 v[196:197], v[20:21], v[152:153], v[160:161]
	v_pk_fma_f32 v[190:191], v[30:31], v[130:131], v[190:191]
	v_pk_fma_f32 v[192:193], v[32:33], v[132:133], v[192:193]
	v_pk_fma_f32 v[194:195], v[26:27], v[146:147], v[194:195]
	v_pk_fma_f32 v[196:197], v[28:29], v[148:149], v[196:197]
	v_pk_fma_f32 v[190:191], v[14:15], v[138:139], v[190:191]
	v_pk_fma_f32 v[192:193], v[16:17], v[140:141], v[192:193]
	v_pk_fma_f32 v[194:195], v[10:11], v[154:155], v[194:195]
	v_pk_fma_f32 v[196:197], v[12:13], v[156:157], v[196:197]
	v_pk_mul_f32 v[198:199], v[190:191], s[50:51]
	v_pk_mul_f32 v[200:201], v[192:193], s[50:51]
	v_exp_f32_e32 v198, v198
	v_exp_f32_e32 v199, v199
	v_exp_f32_e32 v200, v200
	v_exp_f32_e32 v201, v201
	v_add_f32_e32 v198, 1.0, v198
	v_add_f32_e32 v199, 1.0, v199
	v_add_f32_e32 v200, 1.0, v200
	v_add_f32_e32 v201, 1.0, v201
	v_rcp_f32_e32 v198, v198
	v_rcp_f32_e32 v199, v199
	v_rcp_f32_e32 v200, v200
	v_rcp_f32_e32 v201, v201
	v_pk_mul_f32 v[190:191], v[190:191], v[198:199]
	v_pk_mul_f32 v[192:193], v[192:193], v[200:201]
	v_pk_mul_f32 v[190:191], v[190:191], v[194:195]
	v_pk_mul_f32 v[192:193], v[192:193], v[196:197]
	v_cvt_pk_bf16_f32 v234, v190, v191
	v_cvt_pk_bf16_f32 v235, v192, v193
	v_cmp_gt_i32_e32 vcc, s3, v230
	s_and_b64 vcc, vcc, s[52:53]
	s_nop 0
	v_permlane16_swap_b32_e32 v232, v234
	v_permlane16_swap_b32_e32 v233, v235
	s_and_saveexec_b64 s[0:1], vcc
	global_store_dwordx4 v231, v[232:235], s[12:13] offset:128
	s_mov_b64 exec, s[0:1]
	v_pk_fma_f32 v[190:191], v[14:15], v[134:135], v[142:143]
	v_pk_fma_f32 v[192:193], v[16:17], v[136:137], v[144:145]
	v_pk_fma_f32 v[194:195], v[10:11], v[150:151], v[158:159]
	v_pk_fma_f32 v[196:197], v[12:13], v[152:153], v[160:161]
	v_add_u32_e32 v230, 0x7e, v186
	v_add_u32_e32 v231, 0xad400, v187
	v_pk_fma_f32 v[190:191], v[22:23], v[130:131], v[190:191]
	v_pk_fma_f32 v[192:193], v[24:25], v[132:133], v[192:193]
	v_pk_fma_f32 v[194:195], v[18:19], v[146:147], v[194:195]
	v_pk_fma_f32 v[196:197], v[20:21], v[148:149], v[196:197]
	v_pk_fma_f32 v[190:191], v[6:7], v[138:139], v[190:191]
	v_pk_fma_f32 v[192:193], v[8:9], v[140:141], v[192:193]
	v_pk_fma_f32 v[194:195], v[2:3], v[154:155], v[194:195]
	v_pk_fma_f32 v[196:197], v[4:5], v[156:157], v[196:197]
	v_pk_mul_f32 v[198:199], v[190:191], s[50:51]
	v_pk_mul_f32 v[200:201], v[192:193], s[50:51]
	v_exp_f32_e32 v198, v198
	v_exp_f32_e32 v199, v199
	v_exp_f32_e32 v200, v200
	v_exp_f32_e32 v201, v201
	v_add_f32_e32 v198, 1.0, v198
	v_add_f32_e32 v199, 1.0, v199
	v_add_f32_e32 v200, 1.0, v200
	v_add_f32_e32 v201, 1.0, v201
	v_rcp_f32_e32 v198, v198
	v_rcp_f32_e32 v199, v199
	v_rcp_f32_e32 v200, v200
	v_rcp_f32_e32 v201, v201
	v_pk_mul_f32 v[190:191], v[190:191], v[198:199]
	v_pk_mul_f32 v[192:193], v[192:193], v[200:201]
	v_pk_mul_f32 v[190:191], v[190:191], v[194:195]
	v_pk_mul_f32 v[192:193], v[192:193], v[196:197]
	v_cvt_pk_bf16_f32 v232, v190, v191
	v_cvt_pk_bf16_f32 v233, v192, v193
	v_pk_fma_f32 v[190:191], v[6:7], v[134:135], v[142:143]
	v_pk_fma_f32 v[192:193], v[8:9], v[136:137], v[144:145]
	v_pk_fma_f32 v[194:195], v[2:3], v[150:151], v[158:159]
	v_pk_fma_f32 v[196:197], v[4:5], v[152:153], v[160:161]
	v_pk_fma_f32 v[190:191], v[14:15], v[130:131], v[190:191]
	v_pk_fma_f32 v[192:193], v[16:17], v[132:133], v[192:193]
	v_pk_fma_f32 v[194:195], v[10:11], v[146:147], v[194:195]
	v_pk_fma_f32 v[196:197], v[12:13], v[148:149], v[196:197]
	v_fmac_f32_dpp v190, v30, v138 row_ror:15 row_mask:0xf bank_mask:0xf
	v_fmac_f32_dpp v191, v31, v139 row_ror:15 row_mask:0xf bank_mask:0xf
	v_fmac_f32_dpp v192, v32, v140 row_ror:15 row_mask:0xf bank_mask:0xf
	v_fmac_f32_dpp v193, v33, v141 row_ror:15 row_mask:0xf bank_mask:0xf
	v_fmac_f32_dpp v194, v26, v154 row_ror:15 row_mask:0xf bank_mask:0xf
	v_fmac_f32_dpp v195, v27, v155 row_ror:15 row_mask:0xf bank_mask:0xf
	v_fmac_f32_dpp v196, v28, v156 row_ror:15 row_mask:0xf bank_mask:0xf
	v_fmac_f32_dpp v197, v29, v157 row_ror:15 row_mask:0xf bank_mask:0xf
	v_pk_mul_f32 v[198:199], v[190:191], s[50:51]
	v_pk_mul_f32 v[200:201], v[192:193], s[50:51]
	v_exp_f32_e32 v198, v198
	v_exp_f32_e32 v199, v199
	v_exp_f32_e32 v200, v200
	v_exp_f32_e32 v201, v201
	v_add_f32_e32 v198, 1.0, v198
	v_add_f32_e32 v199, 1.0, v199
	v_add_f32_e32 v200, 1.0, v200
	v_add_f32_e32 v201, 1.0, v201
	v_rcp_f32_e32 v198, v198
	v_rcp_f32_e32 v199, v199
	v_rcp_f32_e32 v200, v200
	v_rcp_f32_e32 v201, v201
	v_pk_mul_f32 v[190:191], v[190:191], v[198:199]
	v_pk_mul_f32 v[192:193], v[192:193], v[200:201]
	v_pk_mul_f32 v[190:191], v[190:191], v[194:195]
	v_pk_mul_f32 v[192:193], v[192:193], v[196:197]
	v_cvt_pk_bf16_f32 v234, v190, v191
	v_cvt_pk_bf16_f32 v235, v192, v193
	v_cmp_gt_i32_e32 vcc, s3, v230
	s_and_b64 vcc, vcc, s[54:55]
	s_nop 0
	v_permlane16_swap_b32_e32 v232, v234
	v_permlane16_swap_b32_e32 v233, v235
	s_and_saveexec_b64 s[0:1], vcc
	global_store_dwordx4 v231, v[232:235], s[12:13] offset:128
	s_mov_b64 exec, s[0:1]

.LBB0_181:
	s_add_i32 s88, s44, -2
	s_add_u32 s34, s34, 0x80
	s_addc_u32 s35, s35, 0
	s_add_u32 s89, s42, 0x100
	v_mov_b32_e32 v2, 0
	s_addc_u32 s90, s43, 0
	s_mov_b32 s2, 0
	s_add_i32 s91, s2, 2
	s_add_u32 s12, s34, 0x80
	s_addc_u32 s3, s35, 0
	s_add_i32 s13, 0, 0x10000
	v_add_u32_e32 v142, s13, v183
	ds_read_b128 v[130:133], v142
	ds_read_b128 v[134:137], v142 offset:1024
	ds_read_b128 v[138:141], v142 offset:2048
	ds_read_b128 v[142:145], v142 offset:3072
	s_cmp_eq_u32 s88, s2
	s_cselect_b32 s2, s0, s12
	s_cselect_b32 s3, s1, s3
	s_cselect_b32 s43, s41, s90
	s_cselect_b32 s42, s40, s89
	v_lshl_add_u64 v[190:191], s[34:35], 0, v[174:175]
	s_add_i32 m0, s55, 0xc000
	ds_read_b128 v[146:149], v184
	ds_read_b128 v[150:153], v184 offset:1024
	ds_read_b128 v[154:157], v184 offset:2048
	ds_read_b128 v[158:161], v184 offset:3072
	ds_read_b128 v[162:165], v184 offset:4096
	ds_read_b128 v[166:169], v184 offset:5120
	ds_read_b128 v[178:181], v184 offset:6144
	ds_read_b128 v[186:189], v184 offset:7168
	global_load_lds_dwordx4 v[190:191], off
	v_lshl_add_u64 v[190:191], s[34:35], 0, v[176:177]
	s_add_i32 m0, s55, 0xe000
	s_nop 0
	global_load_lds_dwordx4 v[190:191], off
	s_waitcnt lgkmcnt(8)
	s_add_i32 s92, 0, 0x14000
	s_add_i32 s12, s13, s54
	v_add_u32_e32 v185, s92, v183
	ds_read_b128 v[190:193], v185
	ds_read_b128 v[194:197], v185 offset:1024
	ds_read_b128 v[198:201], v185 offset:2048
	ds_read_b128 v[226:229], v185 offset:3072
	s_barrier
	s_waitcnt lgkmcnt(0)
	s_waitcnt lgkmcnt(0)
	s_nop 0
	v_mfma_f32_16x16x32_bf16 v[126:129], v[130:133], v[146:149], 0
	v_mfma_f32_16x16x32_bf16 v[122:125], v[138:141], v[146:149], 0
	v_mfma_f32_16x16x32_bf16 v[118:121], v[130:133], v[154:157], 0
	v_mfma_f32_16x16x32_bf16 v[114:117], v[138:141], v[154:157], 0
	v_mfma_f32_16x16x32_bf16 v[110:113], v[130:133], v[162:165], 0
	v_mfma_f32_16x16x32_bf16 v[106:109], v[138:141], v[162:165], 0
	v_mfma_f32_16x16x32_bf16 v[102:105], v[130:133], v[178:181], 0
	v_mfma_f32_16x16x32_bf16 v[98:101], v[138:141], v[178:181], 0
	v_mfma_f32_16x16x32_bf16 v[126:129], v[134:137], v[150:153], v[126:129]
	v_mfma_f32_16x16x32_bf16 v[122:125], v[142:145], v[150:153], v[122:125]
	v_mfma_f32_16x16x32_bf16 v[118:121], v[134:137], v[158:161], v[118:121]
	v_mfma_f32_16x16x32_bf16 v[114:117], v[142:145], v[158:161], v[114:117]
	v_mfma_f32_16x16x32_bf16 v[110:113], v[134:137], v[166:169], v[110:113]
	v_mfma_f32_16x16x32_bf16 v[106:109], v[142:145], v[166:169], v[106:109]
	v_mfma_f32_16x16x32_bf16 v[102:105], v[134:137], v[186:189], v[102:105]
	v_mfma_f32_16x16x32_bf16 v[98:101], v[142:145], v[186:189], v[98:101]
	s_waitcnt lgkmcnt(0)
	s_waitcnt lgkmcnt(0)
	v_mfma_f32_16x16x32_bf16 v[62:65], v[190:193], v[146:149], 0
	v_mfma_f32_16x16x32_bf16 v[58:61], v[198:201], v[146:149], 0
	v_mfma_f32_16x16x32_bf16 v[54:57], v[190:193], v[154:157], 0
	v_mfma_f32_16x16x32_bf16 v[50:53], v[198:201], v[154:157], 0
	v_mfma_f32_16x16x32_bf16 v[46:49], v[190:193], v[162:165], 0
	v_mfma_f32_16x16x32_bf16 v[42:45], v[198:201], v[162:165], 0
	v_mfma_f32_16x16x32_bf16 v[38:41], v[190:193], v[178:181], 0
	v_mfma_f32_16x16x32_bf16 v[34:37], v[198:201], v[178:181], 0
	v_mfma_f32_16x16x32_bf16 v[62:65], v[194:197], v[150:153], v[62:65]
	v_mfma_f32_16x16x32_bf16 v[58:61], v[226:229], v[150:153], v[58:61]
	v_mfma_f32_16x16x32_bf16 v[54:57], v[194:197], v[158:161], v[54:57]
	v_mfma_f32_16x16x32_bf16 v[50:53], v[226:229], v[158:161], v[50:53]
	v_mfma_f32_16x16x32_bf16 v[46:49], v[194:197], v[166:169], v[46:49]
	v_mfma_f32_16x16x32_bf16 v[42:45], v[226:229], v[166:169], v[42:45]
	v_mfma_f32_16x16x32_bf16 v[38:41], v[194:197], v[186:189], v[38:41]
	v_mfma_f32_16x16x32_bf16 v[34:37], v[226:229], v[186:189], v[34:37]
	s_mov_b32 m0, s55
	v_lshl_add_u64 v[234:235], s[2:3], 0, v[170:171]
	s_barrier
	ds_read_b128 v[146:149], v184 offset:16384
	ds_read_b128 v[150:153], v184 offset:17408
	ds_read_b128 v[154:157], v184 offset:18432
	ds_read_b128 v[158:161], v184 offset:19456
	ds_read_b128 v[162:165], v184 offset:20480
	ds_read_b128 v[166:169], v184 offset:21504
	ds_read_b128 v[178:181], v184 offset:22528
	ds_read_b128 v[186:189], v184 offset:23552
	global_load_lds_dwordx4 v[234:235], off
	v_lshl_add_u64 v[236:237], s[2:3], 0, v[172:173]
	s_mov_b32 m0, s58
	s_nop 0
	global_load_lds_dwordx4 v[236:237], off
	v_lshl_add_u64 v[230:231], s[42:43], 0, v[170:171]
	s_mov_b32 m0, s12
	s_nop 0
	global_load_lds_dwordx4 v[230:231], off
	v_lshl_add_u64 v[232:233], s[42:43], 0, v[172:173]
	s_add_i32 m0, s12, 0x2000
	s_nop 0
	global_load_lds_dwordx4 v[232:233], off
	s_add_u32 s12, s42, s18
	s_addc_u32 s13, s43, 0
	s_add_i32 s42, s92, s54
	v_lshl_add_u64 v[242:243], s[12:13], 0, v[170:171]
	s_mov_b32 m0, s42
	v_lshl_add_u64 v[244:245], s[12:13], 0, v[172:173]
	global_load_lds_dwordx4 v[242:243], off
	s_add_i32 m0, s42, 0x2000
	s_nop 0
	global_load_lds_dwordx4 v[244:245], off
	s_waitcnt vmcnt(6)
	s_barrier
	s_waitcnt lgkmcnt(0)
	s_waitcnt lgkmcnt(0)
	v_mfma_f32_16x16x32_bf16 v[94:97], v[130:133], v[146:149], 0
	v_mfma_f32_16x16x32_bf16 v[90:93], v[138:141], v[146:149], 0
	v_mfma_f32_16x16x32_bf16 v[86:89], v[130:133], v[154:157], 0
	v_mfma_f32_16x16x32_bf16 v[82:85], v[138:141], v[154:157], 0
	v_mfma_f32_16x16x32_bf16 v[78:81], v[130:133], v[162:165], 0
	v_mfma_f32_16x16x32_bf16 v[74:77], v[138:141], v[162:165], 0
	v_mfma_f32_16x16x32_bf16 v[70:73], v[130:133], v[178:181], 0
	v_mfma_f32_16x16x32_bf16 v[66:69], v[138:141], v[178:181], 0
	v_mfma_f32_16x16x32_bf16 v[94:97], v[134:137], v[150:153], v[94:97]
	v_mfma_f32_16x16x32_bf16 v[90:93], v[142:145], v[150:153], v[90:93]
	v_mfma_f32_16x16x32_bf16 v[86:89], v[134:137], v[158:161], v[86:89]
	v_mfma_f32_16x16x32_bf16 v[82:85], v[142:145], v[158:161], v[82:85]
	v_mfma_f32_16x16x32_bf16 v[78:81], v[134:137], v[166:169], v[78:81]
	v_mfma_f32_16x16x32_bf16 v[74:77], v[142:145], v[166:169], v[74:77]
	v_mfma_f32_16x16x32_bf16 v[70:73], v[134:137], v[186:189], v[70:73]
	v_mfma_f32_16x16x32_bf16 v[66:69], v[142:145], v[186:189], v[66:69]
	v_mfma_f32_16x16x32_bf16 v[30:33], v[190:193], v[146:149], 0
	v_mfma_f32_16x16x32_bf16 v[26:29], v[198:201], v[146:149], 0
	v_mfma_f32_16x16x32_bf16 v[22:25], v[190:193], v[154:157], 0
	v_mfma_f32_16x16x32_bf16 v[18:21], v[198:201], v[154:157], 0
	v_mfma_f32_16x16x32_bf16 v[14:17], v[190:193], v[162:165], 0
	v_mfma_f32_16x16x32_bf16 v[10:13], v[198:201], v[162:165], 0
	v_mfma_f32_16x16x32_bf16 v[6:9], v[190:193], v[178:181], 0
	v_mfma_f32_16x16x32_bf16 v[2:5], v[198:201], v[178:181], 0
	v_mfma_f32_16x16x32_bf16 v[30:33], v[194:197], v[150:153], v[30:33]
	v_mfma_f32_16x16x32_bf16 v[26:29], v[226:229], v[150:153], v[26:29]
	v_mfma_f32_16x16x32_bf16 v[22:25], v[194:197], v[158:161], v[22:25]
	v_mfma_f32_16x16x32_bf16 v[18:21], v[226:229], v[158:161], v[18:21]
	v_mfma_f32_16x16x32_bf16 v[14:17], v[194:197], v[166:169], v[14:17]
	v_mfma_f32_16x16x32_bf16 v[10:13], v[226:229], v[166:169], v[10:13]
	v_mfma_f32_16x16x32_bf16 v[6:9], v[194:197], v[186:189], v[6:9]
	v_mfma_f32_16x16x32_bf16 v[2:5], v[226:229], v[186:189], v[2:5]
	s_add_i32 s12, 0, 0x18000
	v_add_u32_e32 v142, s12, v183
	s_barrier
	ds_read_b128 v[130:133], v142
	ds_read_b128 v[134:137], v142 offset:1024
	ds_read_b128 v[138:141], v142 offset:2048
	ds_read_b128 v[142:145], v142 offset:3072
	s_add_u32 s2, s2, s18
	s_addc_u32 s3, s3, 0
	s_mov_b32 m0, s59
	v_lshl_add_u64 v[190:191], s[2:3], 0, v[170:171]
	ds_read_b128 v[146:149], v184 offset:32768
	ds_read_b128 v[150:153], v184 offset:33792
	ds_read_b128 v[154:157], v184 offset:34816
	ds_read_b128 v[158:161], v184 offset:35840
	ds_read_b128 v[162:165], v184 offset:36864
	ds_read_b128 v[166:169], v184 offset:37888
	ds_read_b128 v[178:181], v184 offset:38912
	ds_read_b128 v[186:189], v184 offset:39936
	global_load_lds_dwordx4 v[190:191], off
	v_lshl_add_u64 v[190:191], s[2:3], 0, v[172:173]
	s_mov_b32 m0, s77
	s_nop 0
	global_load_lds_dwordx4 v[190:191], off
	s_waitcnt lgkmcnt(8)
	s_add_i32 s2, 0, 0x1c000
	s_add_i32 s3, s12, s54
	v_add_u32_e32 v185, s2, v183
	ds_read_b128 v[190:193], v185
	ds_read_b128 v[194:197], v185 offset:1024
	ds_read_b128 v[198:201], v185 offset:2048
	ds_read_b128 v[226:229], v185 offset:3072
	s_barrier
	s_waitcnt lgkmcnt(0)
	s_waitcnt lgkmcnt(0)
	s_nop 0
	v_mfma_f32_16x16x32_bf16 v[126:129], v[130:133], v[146:149], v[126:129]
	v_mfma_f32_16x16x32_bf16 v[122:125], v[138:141], v[146:149], v[122:125]
	v_mfma_f32_16x16x32_bf16 v[118:121], v[130:133], v[154:157], v[118:121]
	v_mfma_f32_16x16x32_bf16 v[114:117], v[138:141], v[154:157], v[114:117]
	v_mfma_f32_16x16x32_bf16 v[110:113], v[130:133], v[162:165], v[110:113]
	v_mfma_f32_16x16x32_bf16 v[106:109], v[138:141], v[162:165], v[106:109]
	v_mfma_f32_16x16x32_bf16 v[102:105], v[130:133], v[178:181], v[102:105]
	v_mfma_f32_16x16x32_bf16 v[98:101], v[138:141], v[178:181], v[98:101]
	v_mfma_f32_16x16x32_bf16 v[126:129], v[134:137], v[150:153], v[126:129]
	v_mfma_f32_16x16x32_bf16 v[122:125], v[142:145], v[150:153], v[122:125]
	v_mfma_f32_16x16x32_bf16 v[118:121], v[134:137], v[158:161], v[118:121]
	v_mfma_f32_16x16x32_bf16 v[114:117], v[142:145], v[158:161], v[114:117]
	v_mfma_f32_16x16x32_bf16 v[110:113], v[134:137], v[166:169], v[110:113]
	v_mfma_f32_16x16x32_bf16 v[106:109], v[142:145], v[166:169], v[106:109]
	v_mfma_f32_16x16x32_bf16 v[102:105], v[134:137], v[186:189], v[102:105]
	v_mfma_f32_16x16x32_bf16 v[98:101], v[142:145], v[186:189], v[98:101]
	s_waitcnt lgkmcnt(0)
	s_waitcnt lgkmcnt(0)
	v_mfma_f32_16x16x32_bf16 v[62:65], v[190:193], v[146:149], v[62:65]
	v_mfma_f32_16x16x32_bf16 v[58:61], v[198:201], v[146:149], v[58:61]
	v_mfma_f32_16x16x32_bf16 v[54:57], v[190:193], v[154:157], v[54:57]
	v_mfma_f32_16x16x32_bf16 v[50:53], v[198:201], v[154:157], v[50:53]
	v_mfma_f32_16x16x32_bf16 v[46:49], v[190:193], v[162:165], v[46:49]
	v_mfma_f32_16x16x32_bf16 v[42:45], v[198:201], v[162:165], v[42:45]
	v_mfma_f32_16x16x32_bf16 v[38:41], v[190:193], v[178:181], v[38:41]
	v_mfma_f32_16x16x32_bf16 v[34:37], v[198:201], v[178:181], v[34:37]
	v_mfma_f32_16x16x32_bf16 v[62:65], v[194:197], v[150:153], v[62:65]
	v_mfma_f32_16x16x32_bf16 v[58:61], v[226:229], v[150:153], v[58:61]
	v_mfma_f32_16x16x32_bf16 v[54:57], v[194:197], v[158:161], v[54:57]
	v_mfma_f32_16x16x32_bf16 v[50:53], v[226:229], v[158:161], v[50:53]
	v_mfma_f32_16x16x32_bf16 v[46:49], v[194:197], v[166:169], v[46:49]
	v_mfma_f32_16x16x32_bf16 v[42:45], v[226:229], v[166:169], v[42:45]
	v_mfma_f32_16x16x32_bf16 v[38:41], v[194:197], v[186:189], v[38:41]
	v_mfma_f32_16x16x32_bf16 v[34:37], v[226:229], v[186:189], v[34:37]
	s_mov_b32 m0, s80
	v_lshl_add_u64 v[234:235], v[234:235], 0, s[20:21]
	s_barrier
	ds_read_b128 v[146:149], v184 offset:49152
	ds_read_b128 v[150:153], v184 offset:50176
	ds_read_b128 v[154:157], v184 offset:51200
	ds_read_b128 v[158:161], v184 offset:52224
	ds_read_b128 v[162:165], v184 offset:53248
	ds_read_b128 v[166:169], v184 offset:54272
	ds_read_b128 v[178:181], v184 offset:55296
	ds_read_b128 v[186:189], v184 offset:56320
	global_load_lds_dwordx4 v[234:235], off
	v_lshl_add_u64 v[236:237], v[236:237], 0, s[20:21]
	s_mov_b32 m0, s81
	s_nop 0
	global_load_lds_dwordx4 v[236:237], off
	v_lshl_add_u64 v[230:231], v[230:231], 0, s[20:21]
	s_mov_b32 m0, s3
	s_nop 0
	global_load_lds_dwordx4 v[230:231], off
	v_lshl_add_u64 v[230:231], v[232:233], 0, s[20:21]
	s_add_i32 m0, s3, 0x2000
	s_nop 0
	global_load_lds_dwordx4 v[230:231], off
	s_add_i32 s2, s2, s54
	v_lshl_add_u64 v[242:243], v[242:243], 0, s[20:21]
	s_mov_b32 m0, s2
	s_nop 0
	global_load_lds_dwordx4 v[242:243], off
	v_lshl_add_u64 v[244:245], v[244:245], 0, s[20:21]
	s_add_i32 m0, s2, 0x2000
	s_nop 0
	global_load_lds_dwordx4 v[244:245], off
	s_waitcnt vmcnt(6)
	s_barrier
	s_waitcnt lgkmcnt(0)
	s_waitcnt lgkmcnt(0)
	s_nop 0
	v_mfma_f32_16x16x32_bf16 v[94:97], v[130:133], v[146:149], v[94:97]
	v_mfma_f32_16x16x32_bf16 v[90:93], v[138:141], v[146:149], v[90:93]
	v_mfma_f32_16x16x32_bf16 v[86:89], v[130:133], v[154:157], v[86:89]
	v_mfma_f32_16x16x32_bf16 v[82:85], v[138:141], v[154:157], v[82:85]
	v_mfma_f32_16x16x32_bf16 v[78:81], v[130:133], v[162:165], v[78:81]
	v_mfma_f32_16x16x32_bf16 v[74:77], v[138:141], v[162:165], v[74:77]
	v_mfma_f32_16x16x32_bf16 v[70:73], v[130:133], v[178:181], v[70:73]
	v_mfma_f32_16x16x32_bf16 v[66:69], v[138:141], v[178:181], v[66:69]
	v_mfma_f32_16x16x32_bf16 v[94:97], v[134:137], v[150:153], v[94:97]
	v_mfma_f32_16x16x32_bf16 v[90:93], v[142:145], v[150:153], v[90:93]
	v_mfma_f32_16x16x32_bf16 v[86:89], v[134:137], v[158:161], v[86:89]
	v_mfma_f32_16x16x32_bf16 v[82:85], v[142:145], v[158:161], v[82:85]
	v_mfma_f32_16x16x32_bf16 v[78:81], v[134:137], v[166:169], v[78:81]
	v_mfma_f32_16x16x32_bf16 v[74:77], v[142:145], v[166:169], v[74:77]
	v_mfma_f32_16x16x32_bf16 v[70:73], v[134:137], v[186:189], v[70:73]
	v_mfma_f32_16x16x32_bf16 v[66:69], v[142:145], v[186:189], v[66:69]
	v_mfma_f32_16x16x32_bf16 v[30:33], v[190:193], v[146:149], v[30:33]
	v_mfma_f32_16x16x32_bf16 v[26:29], v[198:201], v[146:149], v[26:29]
	v_mfma_f32_16x16x32_bf16 v[22:25], v[190:193], v[154:157], v[22:25]
	v_mfma_f32_16x16x32_bf16 v[18:21], v[198:201], v[154:157], v[18:21]
	v_mfma_f32_16x16x32_bf16 v[14:17], v[190:193], v[162:165], v[14:17]
	v_mfma_f32_16x16x32_bf16 v[10:13], v[198:201], v[162:165], v[10:13]
	v_mfma_f32_16x16x32_bf16 v[6:9], v[190:193], v[178:181], v[6:9]
	v_mfma_f32_16x16x32_bf16 v[2:5], v[198:201], v[178:181], v[2:5]
	v_mfma_f32_16x16x32_bf16 v[30:33], v[194:197], v[150:153], v[30:33]
	v_mfma_f32_16x16x32_bf16 v[26:29], v[226:229], v[150:153], v[26:29]
	v_mfma_f32_16x16x32_bf16 v[22:25], v[194:197], v[158:161], v[22:25]
	v_mfma_f32_16x16x32_bf16 v[18:21], v[226:229], v[158:161], v[18:21]
	v_mfma_f32_16x16x32_bf16 v[14:17], v[194:197], v[166:169], v[14:17]
	v_mfma_f32_16x16x32_bf16 v[10:13], v[226:229], v[166:169], v[10:13]
	v_mfma_f32_16x16x32_bf16 v[6:9], v[194:197], v[186:189], v[6:9]
	v_mfma_f32_16x16x32_bf16 v[2:5], v[226:229], v[186:189], v[2:5]
	s_add_u32 s34, s34, 0x100
	s_addc_u32 s35, s35, 0
	s_add_u32 s89, s89, 0x100
	s_addc_u32 s90, s90, 0
	s_cmp_ge_i32 s91, s44
	s_mov_b32 s2, s91
	s_barrier
	s_cbranch_scc1 .Lpeel_x_1

.Lpeel_x_1:
	s_cmp_lt_i32 s86, 64
	s_cselect_b64 s[34:35], -1, 0
	s_ashr_i32 s2, s45, 8
	s_ashr_i32 s3, s2, 31
	s_lshl_b64 s[2:3], s[2:3], 18
	s_add_u32 s2, s2, 0x3232000
	s_addc_u32 s3, s3, 0
	s_cmp_gt_i32 s86, 63
	s_cselect_b32 s12, 0x6000, 0
	s_cselect_b32 s45, s3, 0
	s_cselect_b32 s44, s2, 0
	s_add_u32 s12, s78, s12
	s_addc_u32 s13, s79, 0
	s_lshl_b32 s2, s87, 8
	s_ashr_i32 s3, s2, 31
	s_lshl_b64 s[2:3], s[2:3], 2
	s_add_u32 s12, s12, s2
	s_addc_u32 s13, s13, s3
	v_readlane_b32 s88, v254, 38
	s_add_u32 s42, s12, s88
	s_addc_u32 s43, s13, 0
	global_load_dwordx4 v[134:137], v0, s[42:43]
	global_load_dwordx4 v[130:133], v0, s[42:43] offset:64
	v_lshl_add_u32 v138, s86, 8, v182
	v_ashrrev_i32_e32 v139, 31, v138
	v_readlane_b32 s12, v252, 5
	v_lshlrev_b64 v[138:139], 12, v[138:139]
	v_readlane_b32 s13, v252, 6
	v_readlane_b32 s89, v254, 39
	s_and_b64 vcc, exec, s[34:35]
	v_lshl_add_u64 v[138:139], s[12:13], 0, v[138:139]
	v_lshl_add_u64 v[138:139], v[138:139], 0, s[2:3]
	v_lshl_add_u64 v[138:139], v[138:139], 0, s[88:89]
	v_lshl_add_u64 v[178:179], v[138:139], 0, v[0:1]
	v_lshl_add_u64 v[180:181], v[178:179], 0, s[22:23]
	v_readfirstlane_b32 s88, v178
	v_readfirstlane_b32 s89, v179
	v_and_b32_e32 v178, 15, v202
	v_bfe_u32 v179, v202, 4, 2
	v_lshlrev_b32_e32 v178, 12, v178
	v_lshl_or_b32 v178, v179, 4, v178
	s_mov_b32 s13, 0
	s_and_b64 vcc, exec, s[34:35]
	s_cbranch_vccz .Lre_nf
	v_readlane_b32 s2, v252, 2
	v_readlane_b32 s3, v255, 14
	v_readlane_b32 s12, v255, 12
	s_cmp_eq_u32 s2, 0x100
	s_cbranch_scc0 .Lre_nf
	s_cmp_eq_u32 s3, 5
	s_cbranch_scc1 .Lre_f
	s_cmp_eq_u32 s3, 8
	s_cbranch_scc0 .Lre_nf
